# GEMM epilogue row-ssq cross-row reductions via v_permlane16/32_swap instead of ds_bpermute (80 sites)
# baseline (speedup 1.0000x reference)
; __device__ __forceinline__ float bflo(unsigned u) { return __uint_as_float(u << 16); }
; __device__ __forceinline__ float bfhi(unsigned u) { return __uint_as_float(u & 0xffff0000u); }
; __device__ __forceinline__ unsigned pk2(float lo, float hi) { f32x2_t v = {lo, hi}; bf16x2_t b = __builtin_convertvector(v, bf16x2_t); return __builtin_bit_cast(unsigned, b); }
; __device__ __forceinline__ void atomic_add_agent(float* p, float v) { (void)__hip_atomic_fetch_add(p, v, __ATOMIC_RELAXED, __HIP_MEMORY_SCOPE_AGENT); }
;     __device__ __forceinline__ void operator()(const f32x4 (&acc)[2][2][4][2], const pg8::Unit& u, int wr, int wc, int fr, int fq) const {
;     ...
;                 const int row = row0 + ai * 128 + m * 16; float s2 = 0.f;
; #pragma unroll
;                 for (int bj = 0; bj < 2; ++bj) {
;                     const size_t off = (size_t)row * 1024 + c0 + bj * 128;
;                     f32x4 x0, x1;
;                     if (xin) { x0 = *(const f32x4*)(xin + off); x1 = *(const f32x4*)(xin + off + 4); }
;                     else { const v4u xv = *(const v4u*)(xb + off); x0 = (f32x4){bflo(xv.x), bfhi(xv.x), bflo(xv.y), bfhi(xv.y)}; x1 = (f32x4){bflo(xv.z), bfhi(xv.z), bflo(xv.w), bfhi(xv.w)}; }
;                     const f32x4 n0 = x0 + acc[ai][bj][m][0], n1 = x1 + acc[ai][bj][m][1];
;                     if (xout) { *(f32x4*)(xout + off) = n0; *(f32x4*)(xout + off + 4) = n1; }
;                     else *(v4u*)(xb + off) = (v4u){pk2(n0[0], n0[1]), pk2(n0[2], n0[3]), pk2(n1[0], n1[1]), pk2(n1[2], n1[3])};
;                     s2 += ((n0[0] * n0[0] + n0[1] * n0[1]) + (n0[2] * n0[2] + n0[3] * n0[3])) + ((n1[0] * n1[0] + n1[1] * n1[1]) + (n1[2] * n1[2] + n1[3] * n1[3]));
;                 }
;                 if (ssq) { s2 += __shfl_xor(s2, 16); s2 += __shfl_xor(s2, 32); if (fq == 0) atomic_add_agent(ssq + row, s2); }
.LBB0_467:
	v_lshl_add_u32 v168, s38, 8, v1
	v_lshl_or_b32 v166, s37, 8, v170
	v_ashrrev_i32_e32 v169, 31, v168
	v_ashrrev_i32_e32 v167, 31, v166
	v_lshlrev_b64 v[150:151], 10, v[168:169]
	v_readlane_b32 s2, v255, 22
	v_lshl_add_u64 v[150:151], v[150:151], 0, v[166:167]
	v_readlane_b32 s3, v255, 23
	s_nop 1
	v_lshl_add_u64 v[150:151], v[150:151], 1, s[2:3]
	v_mov_b32_e32 v152, v124
	v_mov_b32_e32 v153, v125
	v_mov_b32_e32 v154, v122
	v_mov_b32_e32 v155, v123
	v_cvt_pk_bf16_f32 v122, v126, v127
	v_cvt_pk_bf16_f32 v123, v128, v129
	v_cvt_pk_bf16_f32 v124, v154, v155
	v_cvt_pk_bf16_f32 v125, v152, v153
	global_store_dwordx4 v[150:151], v[122:125], off
	s_nop 1
	v_mul_f32_e32 v122, v127, v127
	v_mul_f32_e32 v123, v129, v129
	v_fmac_f32_e32 v122, v126, v126
	v_fmac_f32_e32 v123, v128, v128
	v_add_f32_e32 v122, v122, v123
	v_mul_f32_e32 v123, v155, v155
	v_mul_f32_e32 v124, v153, v153
	v_fmac_f32_e32 v123, v154, v154
	v_fmac_f32_e32 v124, v152, v152
	v_add_f32_e32 v123, v123, v124
	v_add_f32_e32 v152, v122, v123
	v_mov_b32_e32 v122, v116
	v_mov_b32_e32 v123, v117
	v_mov_b32_e32 v124, v114
	v_mov_b32_e32 v125, v115
	v_cvt_pk_bf16_f32 v114, v118, v119
	v_cvt_pk_bf16_f32 v115, v120, v121
	v_cvt_pk_bf16_f32 v116, v124, v125
	v_cvt_pk_bf16_f32 v117, v122, v123
	global_store_dwordx4 v[150:151], v[114:117], off offset:256
	s_nop 1
	v_mul_f32_e32 v114, v119, v119
	v_mul_f32_e32 v115, v121, v121
	v_fmac_f32_e32 v114, v118, v118
	v_fmac_f32_e32 v115, v120, v120
	v_add_f32_e32 v114, v114, v115
	v_mul_f32_e32 v115, v125, v125
	v_mul_f32_e32 v116, v123, v123
	v_fmac_f32_e32 v115, v124, v124
	v_fmac_f32_e32 v116, v122, v122
	v_add_f32_e32 v115, v115, v116
	v_and_b32_e32 v116, 64, v191
	v_add_f32_e32 v114, v114, v115
	v_xor_b32_e32 v115, 16, v191
	v_add_u32_e32 v117, 64, v116
	v_cmp_lt_i32_e32 vcc, v115, v117
	v_add_f32_e32 v114, v152, v114
	s_nop 0
	v_cndmask_b32_e32 v115, v191, v115, vcc
	v_lshlrev_b32_e32 v116, 2, v115
	v_mov_b32_e32 v115, v114
	s_nop 1
	v_permlane16_swap_b32_e32 v115, v114
	s_waitcnt lgkmcnt(0)
	v_add_f32_e32 v114, v114, v115
	v_xor_b32_e32 v115, 32, v191
	v_cmp_lt_i32_e32 vcc, v115, v117
	s_nop 1
	v_cndmask_b32_e32 v115, v191, v115, vcc
	v_lshlrev_b32_e32 v117, 2, v115
	v_mov_b32_e32 v115, v114
	s_nop 1
	v_permlane32_swap_b32_e32 v115, v114
	s_and_saveexec_b64 s[2:3], s[0:1]
	s_cbranch_execz .LBB0_469
	v_readlane_b32 s20, v252, 60
	v_readlane_b32 s21, v252, 61
	s_waitcnt lgkmcnt(0)
	v_add_f32_e32 v114, v114, v115
	v_lshl_add_u64 v[118:119], v[168:169], 2, s[20:21]
	global_atomic_add_f32 v[118:119], v114, off
.LBB0_469:
	s_or_b64 exec, exec, s[2:3]
	v_or_b32_e32 v114, 16, v168
	s_waitcnt lgkmcnt(0)
	v_ashrrev_i32_e32 v115, 31, v114
	v_lshlrev_b64 v[118:119], 10, v[114:115]
	v_readlane_b32 s2, v255, 22
	v_lshl_add_u64 v[118:119], v[118:119], 0, v[166:167]
	v_readlane_b32 s3, v255, 23
	s_nop 1
	v_lshl_add_u64 v[122:123], v[118:119], 1, s[2:3]
	v_mov_b32_e32 v118, v108
	v_mov_b32_e32 v119, v109
	v_mov_b32_e32 v120, v106
	v_mov_b32_e32 v121, v107
	v_cvt_pk_bf16_f32 v106, v110, v111
	v_cvt_pk_bf16_f32 v107, v112, v113
	v_cvt_pk_bf16_f32 v108, v120, v121
	v_cvt_pk_bf16_f32 v109, v118, v119
	global_store_dwordx4 v[122:123], v[106:109], off
	s_nop 1
	v_mul_f32_e32 v106, v111, v111
	v_mul_f32_e32 v107, v113, v113
	v_fmac_f32_e32 v106, v110, v110
	v_fmac_f32_e32 v107, v112, v112
	v_add_f32_e32 v106, v106, v107
	v_mul_f32_e32 v107, v121, v121
	v_mul_f32_e32 v108, v119, v119
	v_fmac_f32_e32 v107, v120, v120
	v_fmac_f32_e32 v108, v118, v118
	v_add_f32_e32 v107, v107, v108
	v_add_f32_e32 v118, v106, v107
	v_mov_b32_e32 v106, v100
	v_mov_b32_e32 v107, v101
	v_mov_b32_e32 v108, v98
	v_mov_b32_e32 v109, v99
	v_cvt_pk_bf16_f32 v98, v102, v103
	v_cvt_pk_bf16_f32 v99, v104, v105
	v_cvt_pk_bf16_f32 v100, v108, v109
	v_cvt_pk_bf16_f32 v101, v106, v107
	global_store_dwordx4 v[122:123], v[98:101], off offset:256
	s_nop 1
	v_mul_f32_e32 v98, v103, v103
	v_mul_f32_e32 v99, v105, v105
	v_fmac_f32_e32 v98, v102, v102
	v_fmac_f32_e32 v99, v104, v104
	v_add_f32_e32 v98, v98, v99
	v_mul_f32_e32 v99, v109, v109
	v_mul_f32_e32 v100, v107, v107
	v_fmac_f32_e32 v99, v108, v108
	v_fmac_f32_e32 v100, v106, v106
	v_add_f32_e32 v99, v99, v100
	v_add_f32_e32 v98, v98, v99
	v_add_f32_e32 v98, v118, v98
	v_mov_b32_e32 v99, v98
	s_nop 1
	v_permlane16_swap_b32_e32 v99, v98
	s_waitcnt lgkmcnt(0)
	v_add_f32_e32 v98, v98, v99
	v_mov_b32_e32 v99, v98
	s_nop 1
	v_permlane32_swap_b32_e32 v99, v98
	s_and_saveexec_b64 s[2:3], s[0:1]
	s_cbranch_execz .LBB0_471
	v_readlane_b32 s20, v252, 60
	v_readlane_b32 s21, v252, 61
	s_waitcnt lgkmcnt(0)
	v_add_f32_e32 v98, v98, v99
	v_lshl_add_u64 v[100:101], v[114:115], 2, s[20:21]
	global_atomic_add_f32 v[100:101], v98, off
; __device__ __forceinline__ float bflo(unsigned u) { return __uint_as_float(u << 16); }
; __device__ __forceinline__ float bfhi(unsigned u) { return __uint_as_float(u & 0xffff0000u); }
; __device__ __forceinline__ unsigned pk2(float lo, float hi) { f32x2_t v = {lo, hi}; bf16x2_t b = __builtin_convertvector(v, bf16x2_t); return __builtin_bit_cast(unsigned, b); }
; __device__ __forceinline__ void atomic_add_agent(float* p, float v) { (void)__hip_atomic_fetch_add(p, v, __ATOMIC_RELAXED, __HIP_MEMORY_SCOPE_AGENT); }
;     __device__ __forceinline__ void operator()(const f32x4 (&acc)[2][2][4][2], const pg8::Unit& u, int wr, int wc, int fr, int fq) const {
;     ...
;                 const int row = row0 + ai * 128 + m * 16; float s2 = 0.f;
; #pragma unroll
;                 for (int bj = 0; bj < 2; ++bj) {
;                     const size_t off = (size_t)row * 1024 + c0 + bj * 128;
;                     f32x4 x0, x1;
;                     if (xin) { x0 = *(const f32x4*)(xin + off); x1 = *(const f32x4*)(xin + off + 4); }
;                     else { const v4u xv = *(const v4u*)(xb + off); x0 = (f32x4){bflo(xv.x), bfhi(xv.x), bflo(xv.y), bfhi(xv.y)}; x1 = (f32x4){bflo(xv.z), bfhi(xv.z), bflo(xv.w), bfhi(xv.w)}; }
;                     const f32x4 n0 = x0 + acc[ai][bj][m][0], n1 = x1 + acc[ai][bj][m][1];
;                     if (xout) { *(f32x4*)(xout + off) = n0; *(f32x4*)(xout + off + 4) = n1; }
;                     else *(v4u*)(xb + off) = (v4u){pk2(n0[0], n0[1]), pk2(n0[2], n0[3]), pk2(n1[0], n1[1]), pk2(n1[2], n1[3])};
;                     s2 += ((n0[0] * n0[0] + n0[1] * n0[1]) + (n0[2] * n0[2] + n0[3] * n0[3])) + ((n1[0] * n1[0] + n1[1] * n1[1]) + (n1[2] * n1[2] + n1[3] * n1[3]));
;                 }
;                 if (ssq) { s2 += __shfl_xor(s2, 16); s2 += __shfl_xor(s2, 32); if (fq == 0) atomic_add_agent(ssq + row, s2); }
.LBB0_471:
	s_or_b64 exec, exec, s[2:3]
	v_or_b32_e32 v98, 32, v168
	s_waitcnt lgkmcnt(0)
	v_ashrrev_i32_e32 v99, 31, v98
	v_lshlrev_b64 v[100:101], 10, v[98:99]
	v_readlane_b32 s2, v255, 22
	v_lshl_add_u64 v[100:101], v[100:101], 0, v[166:167]
	v_readlane_b32 s3, v255, 23
	s_nop 1
	v_lshl_add_u64 v[104:105], v[100:101], 1, s[2:3]
	v_mov_b32_e32 v100, v92
	v_mov_b32_e32 v101, v93
	v_mov_b32_e32 v102, v90
	v_mov_b32_e32 v103, v91
	v_cvt_pk_bf16_f32 v90, v94, v95
	v_cvt_pk_bf16_f32 v91, v96, v97
	v_cvt_pk_bf16_f32 v92, v102, v103
	v_cvt_pk_bf16_f32 v93, v100, v101
	global_store_dwordx4 v[104:105], v[90:93], off
	s_nop 1
	v_mul_f32_e32 v90, v95, v95
	v_mul_f32_e32 v91, v97, v97
	v_fmac_f32_e32 v90, v94, v94
	v_fmac_f32_e32 v91, v96, v96
	v_add_f32_e32 v90, v90, v91
	v_mul_f32_e32 v91, v103, v103
	v_mul_f32_e32 v92, v101, v101
	v_fmac_f32_e32 v91, v102, v102
	v_fmac_f32_e32 v92, v100, v100
	v_add_f32_e32 v91, v91, v92
	v_add_f32_e32 v100, v90, v91
	v_mov_b32_e32 v90, v84
	v_mov_b32_e32 v91, v85
	v_mov_b32_e32 v92, v82
	v_mov_b32_e32 v93, v83
	v_cvt_pk_bf16_f32 v82, v86, v87
	v_cvt_pk_bf16_f32 v83, v88, v89
	v_cvt_pk_bf16_f32 v84, v92, v93
	v_cvt_pk_bf16_f32 v85, v90, v91
	global_store_dwordx4 v[104:105], v[82:85], off offset:256
	s_nop 1
	v_mul_f32_e32 v82, v87, v87
	v_mul_f32_e32 v83, v89, v89
	v_fmac_f32_e32 v82, v86, v86
	v_fmac_f32_e32 v83, v88, v88
	v_add_f32_e32 v82, v82, v83
	v_mul_f32_e32 v83, v93, v93
	v_mul_f32_e32 v84, v91, v91
	v_fmac_f32_e32 v83, v92, v92
	v_fmac_f32_e32 v84, v90, v90
	v_add_f32_e32 v83, v83, v84
	v_add_f32_e32 v82, v82, v83
	v_add_f32_e32 v82, v100, v82
	v_mov_b32_e32 v83, v82
	s_nop 1
	v_permlane16_swap_b32_e32 v83, v82
	s_waitcnt lgkmcnt(0)
	v_add_f32_e32 v82, v82, v83
	v_mov_b32_e32 v83, v82
	s_nop 1
	v_permlane32_swap_b32_e32 v83, v82
	s_and_saveexec_b64 s[2:3], s[0:1]
	s_cbranch_execz .LBB0_473
	v_readlane_b32 s20, v252, 60
	v_readlane_b32 s21, v252, 61
	s_waitcnt lgkmcnt(0)
	v_add_f32_e32 v82, v82, v83
	v_lshl_add_u64 v[84:85], v[98:99], 2, s[20:21]
	global_atomic_add_f32 v[84:85], v82, off
.LBB0_473:
	s_or_b64 exec, exec, s[2:3]
	v_or_b32_e32 v82, 48, v168
	s_waitcnt lgkmcnt(0)
	v_ashrrev_i32_e32 v83, 31, v82
	v_lshlrev_b64 v[84:85], 10, v[82:83]
	v_readlane_b32 s2, v255, 22
	v_lshl_add_u64 v[84:85], v[84:85], 0, v[166:167]
	v_readlane_b32 s3, v255, 23
	s_nop 1
	v_lshl_add_u64 v[88:89], v[84:85], 1, s[2:3]
	v_mov_b32_e32 v84, v76
	v_mov_b32_e32 v85, v77
	v_mov_b32_e32 v86, v74
	v_mov_b32_e32 v87, v75
	v_cvt_pk_bf16_f32 v74, v78, v79
	v_cvt_pk_bf16_f32 v75, v80, v81
	v_cvt_pk_bf16_f32 v76, v86, v87
	v_cvt_pk_bf16_f32 v77, v84, v85
	global_store_dwordx4 v[88:89], v[74:77], off
	s_nop 1
	v_mul_f32_e32 v74, v79, v79
	v_mul_f32_e32 v75, v81, v81
	v_fmac_f32_e32 v74, v78, v78
	v_fmac_f32_e32 v75, v80, v80
	v_add_f32_e32 v74, v74, v75
	v_mul_f32_e32 v75, v87, v87
	v_mul_f32_e32 v76, v85, v85
	v_fmac_f32_e32 v75, v86, v86
	v_fmac_f32_e32 v76, v84, v84
	v_add_f32_e32 v75, v75, v76
	v_add_f32_e32 v84, v74, v75
	v_mov_b32_e32 v74, v68
	v_mov_b32_e32 v75, v69
	v_mov_b32_e32 v76, v66
	v_mov_b32_e32 v77, v67
	v_cvt_pk_bf16_f32 v66, v70, v71
	v_cvt_pk_bf16_f32 v67, v72, v73
	v_cvt_pk_bf16_f32 v68, v76, v77
	v_cvt_pk_bf16_f32 v69, v74, v75
	global_store_dwordx4 v[88:89], v[66:69], off offset:256
	s_nop 1
	v_mul_f32_e32 v66, v71, v71
	v_mul_f32_e32 v67, v73, v73
	v_fmac_f32_e32 v66, v70, v70
	v_fmac_f32_e32 v67, v72, v72
	v_add_f32_e32 v66, v66, v67
	v_mul_f32_e32 v67, v77, v77
	v_mul_f32_e32 v68, v75, v75
	v_fmac_f32_e32 v67, v76, v76
	v_fmac_f32_e32 v68, v74, v74
	v_add_f32_e32 v67, v67, v68
	v_add_f32_e32 v66, v66, v67
	v_add_f32_e32 v66, v84, v66
	v_mov_b32_e32 v67, v66
	s_nop 1
	v_permlane16_swap_b32_e32 v67, v66
	s_waitcnt lgkmcnt(0)
	v_add_f32_e32 v66, v66, v67
	v_mov_b32_e32 v67, v66
	s_nop 1
	v_permlane32_swap_b32_e32 v67, v66
	s_and_saveexec_b64 s[2:3], s[0:1]
	s_cbranch_execz .LBB0_475
	v_readlane_b32 s20, v252, 60
	v_readlane_b32 s21, v252, 61
	s_waitcnt lgkmcnt(0)
	v_add_f32_e32 v66, v66, v67
	v_lshl_add_u64 v[68:69], v[82:83], 2, s[20:21]
	global_atomic_add_f32 v[68:69], v66, off
.LBB0_475:
	s_or_b64 exec, exec, s[2:3]
	v_add_u32_e32 v66, 0x80, v168
	s_waitcnt lgkmcnt(0)
	v_ashrrev_i32_e32 v67, 31, v66
	v_lshlrev_b64 v[68:69], 10, v[66:67]
	v_readlane_b32 s2, v255, 22
	v_lshl_add_u64 v[68:69], v[68:69], 0, v[166:167]
	v_readlane_b32 s3, v255, 23
	s_nop 1
	v_lshl_add_u64 v[72:73], v[68:69], 1, s[2:3]
	v_mov_b32_e32 v68, v60
	v_mov_b32_e32 v69, v61
	v_mov_b32_e32 v70, v58
	v_mov_b32_e32 v71, v59
	v_cvt_pk_bf16_f32 v58, v62, v63
	v_cvt_pk_bf16_f32 v59, v64, v65
	v_cvt_pk_bf16_f32 v60, v70, v71
	v_cvt_pk_bf16_f32 v61, v68, v69
	global_store_dwordx4 v[72:73], v[58:61], off
	s_nop 1
	v_mul_f32_e32 v58, v63, v63
	v_mul_f32_e32 v59, v65, v65
	v_fmac_f32_e32 v58, v62, v62
	v_fmac_f32_e32 v59, v64, v64
	v_add_f32_e32 v58, v58, v59
	v_mul_f32_e32 v59, v71, v71
	v_mul_f32_e32 v60, v69, v69
	v_fmac_f32_e32 v59, v70, v70
	v_fmac_f32_e32 v60, v68, v68
	v_add_f32_e32 v59, v59, v60
	v_add_f32_e32 v68, v58, v59
	v_mov_b32_e32 v58, v52
	v_mov_b32_e32 v59, v53
	v_mov_b32_e32 v60, v50
	v_mov_b32_e32 v61, v51
	v_cvt_pk_bf16_f32 v50, v54, v55
	v_cvt_pk_bf16_f32 v51, v56, v57
	v_cvt_pk_bf16_f32 v52, v60, v61
	v_cvt_pk_bf16_f32 v53, v58, v59
	global_store_dwordx4 v[72:73], v[50:53], off offset:256
	s_nop 1
	v_mul_f32_e32 v50, v55, v55
	v_mul_f32_e32 v51, v57, v57
	v_fmac_f32_e32 v50, v54, v54
	v_fmac_f32_e32 v51, v56, v56
	v_add_f32_e32 v50, v50, v51
	v_mul_f32_e32 v51, v61, v61
	v_mul_f32_e32 v52, v59, v59
	v_fmac_f32_e32 v51, v60, v60
	v_fmac_f32_e32 v52, v58, v58
	v_add_f32_e32 v51, v51, v52
	v_add_f32_e32 v50, v50, v51
	v_add_f32_e32 v50, v68, v50
	v_mov_b32_e32 v51, v50
	s_nop 1
	v_permlane16_swap_b32_e32 v51, v50
	s_waitcnt lgkmcnt(0)
	v_add_f32_e32 v50, v50, v51
	v_mov_b32_e32 v51, v50
	s_nop 1
	v_permlane32_swap_b32_e32 v51, v50
	s_and_saveexec_b64 s[2:3], s[0:1]
	s_cbranch_execz .LBB0_477
	v_readlane_b32 s20, v252, 60
	v_readlane_b32 s21, v252, 61
	s_waitcnt lgkmcnt(0)
	v_add_f32_e32 v50, v50, v51
	v_lshl_add_u64 v[52:53], v[66:67], 2, s[20:21]
	global_atomic_add_f32 v[52:53], v50, off
; __device__ __forceinline__ float bflo(unsigned u) { return __uint_as_float(u << 16); }
; __device__ __forceinline__ float bfhi(unsigned u) { return __uint_as_float(u & 0xffff0000u); }
; __device__ __forceinline__ unsigned pk2(float lo, float hi) { f32x2_t v = {lo, hi}; bf16x2_t b = __builtin_convertvector(v, bf16x2_t); return __builtin_bit_cast(unsigned, b); }
; __device__ __forceinline__ void atomic_add_agent(float* p, float v) { (void)__hip_atomic_fetch_add(p, v, __ATOMIC_RELAXED, __HIP_MEMORY_SCOPE_AGENT); }
;     __device__ __forceinline__ void operator()(const f32x4 (&acc)[2][2][4][2], const pg8::Unit& u, int wr, int wc, int fr, int fq) const {
;     ...
;                 const int row = row0 + ai * 128 + m * 16; float s2 = 0.f;
; #pragma unroll
;                 for (int bj = 0; bj < 2; ++bj) {
;                     const size_t off = (size_t)row * 1024 + c0 + bj * 128;
;                     f32x4 x0, x1;
;                     if (xin) { x0 = *(const f32x4*)(xin + off); x1 = *(const f32x4*)(xin + off + 4); }
;                     else { const v4u xv = *(const v4u*)(xb + off); x0 = (f32x4){bflo(xv.x), bfhi(xv.x), bflo(xv.y), bfhi(xv.y)}; x1 = (f32x4){bflo(xv.z), bfhi(xv.z), bflo(xv.w), bfhi(xv.w)}; }
;                     const f32x4 n0 = x0 + acc[ai][bj][m][0], n1 = x1 + acc[ai][bj][m][1];
;                     if (xout) { *(f32x4*)(xout + off) = n0; *(f32x4*)(xout + off + 4) = n1; }
;                     else *(v4u*)(xb + off) = (v4u){pk2(n0[0], n0[1]), pk2(n0[2], n0[3]), pk2(n1[0], n1[1]), pk2(n1[2], n1[3])};
;                     s2 += ((n0[0] * n0[0] + n0[1] * n0[1]) + (n0[2] * n0[2] + n0[3] * n0[3])) + ((n1[0] * n1[0] + n1[1] * n1[1]) + (n1[2] * n1[2] + n1[3] * n1[3]));
;                 }
;                 if (ssq) { s2 += __shfl_xor(s2, 16); s2 += __shfl_xor(s2, 32); if (fq == 0) atomic_add_agent(ssq + row, s2); }
.LBB0_477:
	s_or_b64 exec, exec, s[2:3]
	v_add_u32_e32 v50, 0x90, v168
	s_waitcnt lgkmcnt(0)
	v_ashrrev_i32_e32 v51, 31, v50
	v_lshlrev_b64 v[52:53], 10, v[50:51]
	v_readlane_b32 s2, v255, 22
	v_lshl_add_u64 v[52:53], v[52:53], 0, v[166:167]
	v_readlane_b32 s3, v255, 23
	s_nop 1
	v_lshl_add_u64 v[56:57], v[52:53], 1, s[2:3]
	v_mov_b32_e32 v52, v44
	v_mov_b32_e32 v53, v45
	v_mov_b32_e32 v54, v42
	v_mov_b32_e32 v55, v43
	v_cvt_pk_bf16_f32 v42, v46, v47
	v_cvt_pk_bf16_f32 v43, v48, v49
	v_cvt_pk_bf16_f32 v44, v54, v55
	v_cvt_pk_bf16_f32 v45, v52, v53
	global_store_dwordx4 v[56:57], v[42:45], off
	s_nop 1
	v_mul_f32_e32 v42, v47, v47
	v_mul_f32_e32 v43, v49, v49
	v_fmac_f32_e32 v42, v46, v46
	v_fmac_f32_e32 v43, v48, v48
	v_add_f32_e32 v42, v42, v43
	v_mul_f32_e32 v43, v55, v55
	v_mul_f32_e32 v44, v53, v53
	v_fmac_f32_e32 v43, v54, v54
	v_fmac_f32_e32 v44, v52, v52
	v_add_f32_e32 v43, v43, v44
	v_add_f32_e32 v52, v42, v43
	v_mov_b32_e32 v42, v36
	v_mov_b32_e32 v43, v37
	v_mov_b32_e32 v44, v34
	v_mov_b32_e32 v45, v35
	v_cvt_pk_bf16_f32 v34, v38, v39
	v_cvt_pk_bf16_f32 v35, v40, v41
	v_cvt_pk_bf16_f32 v36, v44, v45
	v_cvt_pk_bf16_f32 v37, v42, v43
	global_store_dwordx4 v[56:57], v[34:37], off offset:256
	s_nop 1
	v_mul_f32_e32 v34, v39, v39
	v_mul_f32_e32 v35, v41, v41
	v_fmac_f32_e32 v34, v38, v38
	v_fmac_f32_e32 v35, v40, v40
	v_add_f32_e32 v34, v34, v35
	v_mul_f32_e32 v35, v45, v45
	v_mul_f32_e32 v36, v43, v43
	v_fmac_f32_e32 v35, v44, v44
	v_fmac_f32_e32 v36, v42, v42
	v_add_f32_e32 v35, v35, v36
	v_add_f32_e32 v34, v34, v35
	v_add_f32_e32 v34, v52, v34
	v_mov_b32_e32 v35, v34
	s_nop 1
	v_permlane16_swap_b32_e32 v35, v34
	s_waitcnt lgkmcnt(0)
	v_add_f32_e32 v34, v34, v35
	v_mov_b32_e32 v35, v34
	s_nop 1
	v_permlane32_swap_b32_e32 v35, v34
	s_and_saveexec_b64 s[2:3], s[0:1]
	s_cbranch_execz .LBB0_479
	v_readlane_b32 s20, v252, 60
	v_readlane_b32 s21, v252, 61
	s_waitcnt lgkmcnt(0)
	v_add_f32_e32 v34, v34, v35
	v_lshl_add_u64 v[36:37], v[50:51], 2, s[20:21]
	global_atomic_add_f32 v[36:37], v34, off
.LBB0_479:
	s_or_b64 exec, exec, s[2:3]
	v_add_u32_e32 v34, 0xa0, v168
	s_waitcnt lgkmcnt(0)
	v_ashrrev_i32_e32 v35, 31, v34
	v_lshlrev_b64 v[36:37], 10, v[34:35]
	v_readlane_b32 s2, v255, 22
	v_lshl_add_u64 v[36:37], v[36:37], 0, v[166:167]
	v_readlane_b32 s3, v255, 23
	s_nop 1
	v_lshl_add_u64 v[40:41], v[36:37], 1, s[2:3]
	v_mov_b32_e32 v36, v28
	v_mov_b32_e32 v37, v29
	v_mov_b32_e32 v38, v26
	v_mov_b32_e32 v39, v27
	v_cvt_pk_bf16_f32 v26, v30, v31
	v_cvt_pk_bf16_f32 v27, v32, v33
	v_cvt_pk_bf16_f32 v28, v38, v39
	v_cvt_pk_bf16_f32 v29, v36, v37
	global_store_dwordx4 v[40:41], v[26:29], off
	s_nop 1
	v_mul_f32_e32 v26, v31, v31
	v_mul_f32_e32 v27, v33, v33
	v_fmac_f32_e32 v26, v30, v30
	v_fmac_f32_e32 v27, v32, v32
	v_add_f32_e32 v26, v26, v27
	v_mul_f32_e32 v27, v39, v39
	v_mul_f32_e32 v28, v37, v37
	v_fmac_f32_e32 v27, v38, v38
	v_fmac_f32_e32 v28, v36, v36
	v_add_f32_e32 v27, v27, v28
	v_add_f32_e32 v36, v26, v27
	v_mov_b32_e32 v26, v20
	v_mov_b32_e32 v27, v21
	v_mov_b32_e32 v28, v18
	v_mov_b32_e32 v29, v19
	v_cvt_pk_bf16_f32 v18, v22, v23
	v_cvt_pk_bf16_f32 v19, v24, v25
	v_cvt_pk_bf16_f32 v20, v28, v29
	v_cvt_pk_bf16_f32 v21, v26, v27
	global_store_dwordx4 v[40:41], v[18:21], off offset:256
	s_nop 1
	v_mul_f32_e32 v18, v23, v23
	v_mul_f32_e32 v19, v25, v25
	v_fmac_f32_e32 v18, v22, v22
	v_fmac_f32_e32 v19, v24, v24
	v_add_f32_e32 v18, v18, v19
	v_mul_f32_e32 v19, v29, v29
	v_mul_f32_e32 v20, v27, v27
	v_fmac_f32_e32 v19, v28, v28
	v_fmac_f32_e32 v20, v26, v26
	v_add_f32_e32 v19, v19, v20
	v_add_f32_e32 v18, v18, v19
	v_add_f32_e32 v18, v36, v18
	v_mov_b32_e32 v19, v18
	s_nop 1
	v_permlane16_swap_b32_e32 v19, v18
	s_waitcnt lgkmcnt(0)
	v_add_f32_e32 v18, v18, v19
	v_mov_b32_e32 v19, v18
	s_nop 1
	v_permlane32_swap_b32_e32 v19, v18
	s_and_saveexec_b64 s[2:3], s[0:1]
	s_cbranch_execz .LBB0_481
	v_readlane_b32 s20, v252, 60
	v_readlane_b32 s21, v252, 61
	s_waitcnt lgkmcnt(0)
	v_add_f32_e32 v18, v18, v19
	v_lshl_add_u64 v[20:21], v[34:35], 2, s[20:21]
	global_atomic_add_f32 v[20:21], v18, off
.LBB0_481:
	s_or_b64 exec, exec, s[2:3]
	v_add_u32_e32 v18, 0xb0, v168
	s_waitcnt lgkmcnt(0)
	v_ashrrev_i32_e32 v19, 31, v18
	v_lshlrev_b64 v[20:21], 10, v[18:19]
	v_readlane_b32 s2, v255, 22
	v_lshl_add_u64 v[20:21], v[20:21], 0, v[166:167]
	v_readlane_b32 s3, v255, 23
	s_nop 1
	v_lshl_add_u64 v[24:25], v[20:21], 1, s[2:3]
	v_mov_b32_e32 v20, v12
	v_mov_b32_e32 v21, v13
	v_mov_b32_e32 v22, v10
	v_mov_b32_e32 v23, v11
	v_cvt_pk_bf16_f32 v10, v14, v15
	v_cvt_pk_bf16_f32 v11, v16, v17
	v_cvt_pk_bf16_f32 v12, v22, v23
	v_cvt_pk_bf16_f32 v13, v20, v21
	global_store_dwordx4 v[24:25], v[10:13], off
	s_nop 1
	v_mul_f32_e32 v10, v15, v15
	v_mul_f32_e32 v11, v17, v17
	v_fmac_f32_e32 v10, v14, v14
	v_fmac_f32_e32 v11, v16, v16
	v_add_f32_e32 v10, v10, v11
	v_mul_f32_e32 v11, v23, v23
	v_mul_f32_e32 v12, v21, v21
	v_fmac_f32_e32 v11, v22, v22
	v_fmac_f32_e32 v12, v20, v20
	v_add_f32_e32 v11, v11, v12
	v_add_f32_e32 v20, v10, v11
	v_mov_b32_e32 v10, v4
	v_mov_b32_e32 v11, v5
	v_mov_b32_e32 v12, v2
	v_mov_b32_e32 v13, v3
	v_cvt_pk_bf16_f32 v2, v6, v7
	v_cvt_pk_bf16_f32 v3, v8, v9
	v_cvt_pk_bf16_f32 v4, v12, v13
	v_cvt_pk_bf16_f32 v5, v10, v11
	global_store_dwordx4 v[24:25], v[2:5], off offset:256
	s_nop 1
	v_mul_f32_e32 v2, v7, v7
	v_mul_f32_e32 v3, v9, v9
	v_fmac_f32_e32 v2, v6, v6
	v_fmac_f32_e32 v3, v8, v8
	v_add_f32_e32 v2, v2, v3
	v_mul_f32_e32 v3, v13, v13
	v_mul_f32_e32 v4, v11, v11
	v_fmac_f32_e32 v3, v12, v12
	v_fmac_f32_e32 v4, v10, v10
	v_add_f32_e32 v3, v3, v4
	v_add_f32_e32 v2, v2, v3
	v_add_f32_e32 v2, v20, v2
	v_mov_b32_e32 v3, v2
	s_nop 1
	v_permlane16_swap_b32_e32 v3, v2
	s_waitcnt lgkmcnt(0)
	v_add_f32_e32 v2, v2, v3
	v_mov_b32_e32 v3, v2
	s_nop 1
	v_permlane32_swap_b32_e32 v3, v2
	s_and_saveexec_b64 s[2:3], s[0:1]
	s_cbranch_execz .LBB0_483
	v_readlane_b32 s20, v252, 60
	v_readlane_b32 s21, v252, 61
	s_waitcnt lgkmcnt(0)
	v_add_f32_e32 v2, v2, v3
	v_lshl_add_u64 v[4:5], v[18:19], 2, s[20:21]
	global_atomic_add_f32 v[4:5], v2, off

; __device__ __forceinline__ float silu_f(float x) { return x * __builtin_amdgcn_rcpf(1.f + __expf(-x)); }
; __device__ __forceinline__ float gelu_f(float x) { const float u2 = 1.5957691216057308f * (x + 0.044715f * x * x * x); return x * __builtin_amdgcn_rcpf(1.f + __expf(-u2)); }
; __device__ __forceinline__ void atomic_add_agent(float* p, float v) { (void)__hip_atomic_fetch_add(p, v, __ATOMIC_RELAXED, __HIP_MEMORY_SCOPE_AGENT); }
; __device__ __forceinline__ v4u pack8(const float (&y)[8]) { return (v4u){pk2(y[0], y[1]), pk2(y[2], y[3]), pk2(y[4], y[5]), pk2(y[6], y[7])}; }
;     __device__ __forceinline__ void operator()(const f32x4 (&acc)[2][2][4][2], const pg8::Unit& u, int wr, int wc, int fr, int fq) const {
;     ...
;                         } else if (region == 1) {
; #pragma unroll
;                             for (int j = 0; j < 8; ++j) { y[j] = gelu_f(v[j]); s1 += y[j]; s2 += y[j] * y[j]; }
;                             *(v4u*)(o1 + off) = pack8(y);
;                         } else {
; #pragma unroll
;                             for (int j = 0; j < 8; ++j) y[j] = silu_f(v[j]);
;                             *(v4u*)(Y + off) = pack8(y);
;                         }
;                     }
;                     if (region == 1) {
;                         s1 += __shfl_xor(s1, 16); s1 += __shfl_xor(s1, 32); s2 += __shfl_xor(s2, 16); s2 += __shfl_xor(s2, 32);
;                         if (fq == 0) { atomic_add_agent(vs1 + row, s1); atomic_add_agent(vs2 + row, s2); }
;                     }
.LBB0_562:
	v_lshlrev_b64 v[118:119], 10, v[166:167]
	v_lshl_add_u64 v[118:119], v[118:119], 1, s[2:3]
	v_mov_b32_e32 v123, v0
	v_cndmask_b32_e64 v1, 0, 1, s[0:1]
	v_cvt_pk_bf16_f32 v114, v126, v127
	v_cvt_pk_bf16_f32 v115, v128, v129
	v_cvt_pk_bf16_f32 v116, v170, v171
	v_cvt_pk_bf16_f32 v117, v174, v175
	v_lshl_add_u64 v[118:119], v[118:119], 0, v[122:123]
	v_cmp_ne_u32_e64 s[50:51], 1, v1
	s_andn2_b64 vcc, exec, s[0:1]
	global_store_dwordx4 v[118:119], v[114:117], off offset:256
	s_cbranch_vccnz .LBB0_566
	s_nop 0
	v_and_b32_e32 v114, 64, v191
	v_xor_b32_e32 v1, 16, v191
	v_add_u32_e32 v114, 64, v114
	v_cmp_lt_i32_e32 vcc, v1, v114
	v_xor_b32_e32 v116, 32, v191
	s_nop 0
	v_cndmask_b32_e32 v1, v191, v1, vcc
	v_lshlrev_b32_e32 v115, 2, v1
	v_mov_b32_e32 v1, v173
	s_nop 1
	v_permlane16_swap_b32_e32 v1, v173
	v_mov_b32_e32 v115, v172
	s_nop 1
	v_permlane16_swap_b32_e32 v115, v172
	v_cmp_lt_i32_e32 vcc, v116, v114
	s_waitcnt lgkmcnt(1)
	v_add_f32_e32 v1, v173, v1
	v_cndmask_b32_e32 v114, v191, v116, vcc
	v_lshlrev_b32_e32 v116, 2, v114
	s_waitcnt lgkmcnt(0)
	v_add_f32_e32 v115, v172, v115
	v_mov_b32_e32 v114, v1
	s_nop 1
	v_permlane32_swap_b32_e32 v114, v1
	v_mov_b32_e32 v116, v115
	s_nop 1
	v_permlane32_swap_b32_e32 v116, v115
	s_and_saveexec_b64 s[0:1], s[42:43]
	s_cbranch_execz .LBB0_565
	v_readlane_b32 s2, v251, 23
	v_lshlrev_b64 v[118:119], 2, v[166:167]
	v_readlane_b32 s3, v251, 24
	s_waitcnt lgkmcnt(1)
	v_add_f32_e32 v1, v1, v114
	s_waitcnt lgkmcnt(0)
	v_add_f32_e32 v114, v115, v116
	v_lshl_add_u64 v[120:121], s[2:3], 0, v[118:119]
	v_readlane_b32 s2, v251, 21
	v_readlane_b32 s3, v251, 22
	s_nop 1
	v_lshl_add_u64 v[118:119], s[2:3], 0, v[118:119]
	global_atomic_add_f32 v[118:119], v1, off
	global_atomic_add_f32 v[120:121], v114, off

; __device__ __forceinline__ float silu_f(float x) { return x * __builtin_amdgcn_rcpf(1.f + __expf(-x)); }
; __device__ __forceinline__ float gelu_f(float x) { const float u2 = 1.5957691216057308f * (x + 0.044715f * x * x * x); return x * __builtin_amdgcn_rcpf(1.f + __expf(-u2)); }
; __device__ __forceinline__ void atomic_add_agent(float* p, float v) { (void)__hip_atomic_fetch_add(p, v, __ATOMIC_RELAXED, __HIP_MEMORY_SCOPE_AGENT); }
; __device__ __forceinline__ v4u pack8(const float (&y)[8]) { return (v4u){pk2(y[0], y[1]), pk2(y[2], y[3]), pk2(y[4], y[5]), pk2(y[6], y[7])}; }
;     __device__ __forceinline__ void operator()(const f32x4 (&acc)[2][2][4][2], const pg8::Unit& u, int wr, int wc, int fr, int fq) const {
;     ...
;                         } else if (region == 1) {
; #pragma unroll
;                             for (int j = 0; j < 8; ++j) { y[j] = gelu_f(v[j]); s1 += y[j]; s2 += y[j] * y[j]; }
;                             *(v4u*)(o1 + off) = pack8(y);
;                         } else {
; #pragma unroll
;                             for (int j = 0; j < 8; ++j) y[j] = silu_f(v[j]);
;                             *(v4u*)(Y + off) = pack8(y);
;                         }
;                     }
;                     if (region == 1) {
;                         s1 += __shfl_xor(s1, 16); s1 += __shfl_xor(s1, 32); s2 += __shfl_xor(s2, 16); s2 += __shfl_xor(s2, 32);
;                         if (fq == 0) { atomic_add_agent(vs1 + row, s1); atomic_add_agent(vs2 + row, s2); }
;                     }
.LBB0_581:
	v_lshlrev_b64 v[102:103], 10, v[114:115]
	v_lshl_add_u64 v[102:103], v[102:103], 1, s[0:1]
	v_mov_b32_e32 v123, v0
	v_cvt_pk_bf16_f32 v98, v108, v109
	v_cvt_pk_bf16_f32 v99, v110, v111
	v_cvt_pk_bf16_f32 v100, v112, v113
	v_cvt_pk_bf16_f32 v101, v118, v119
	v_lshl_add_u64 v[102:103], v[102:103], 0, v[122:123]
	s_and_b64 vcc, exec, s[50:51]
	global_store_dwordx4 v[102:103], v[98:101], off offset:256
	s_cbranch_vccnz .LBB0_585
	s_nop 0
	v_and_b32_e32 v98, 64, v191
	v_xor_b32_e32 v1, 16, v191
	v_add_u32_e32 v98, 64, v98
	v_cmp_lt_i32_e32 vcc, v1, v98
	v_xor_b32_e32 v100, 32, v191
	s_nop 0
	v_cndmask_b32_e32 v1, v191, v1, vcc
	v_lshlrev_b32_e32 v99, 2, v1
	v_mov_b32_e32 v1, v117
	s_nop 1
	v_permlane16_swap_b32_e32 v1, v117
	v_mov_b32_e32 v99, v116
	s_nop 1
	v_permlane16_swap_b32_e32 v99, v116
	v_cmp_lt_i32_e32 vcc, v100, v98
	s_waitcnt lgkmcnt(1)
	v_add_f32_e32 v1, v117, v1
	v_cndmask_b32_e32 v98, v191, v100, vcc
	v_lshlrev_b32_e32 v100, 2, v98
	s_waitcnt lgkmcnt(0)
	v_add_f32_e32 v99, v116, v99
	v_mov_b32_e32 v98, v1
	s_nop 1
	v_permlane32_swap_b32_e32 v98, v1
	v_mov_b32_e32 v100, v99
	s_nop 1
	v_permlane32_swap_b32_e32 v100, v99
	s_and_saveexec_b64 s[0:1], s[42:43]
	s_cbranch_execz .LBB0_584
	v_readlane_b32 s2, v251, 23
	v_lshlrev_b64 v[102:103], 2, v[114:115]
	v_readlane_b32 s3, v251, 24
	s_waitcnt lgkmcnt(1)
	v_add_f32_e32 v1, v1, v98
	s_waitcnt lgkmcnt(0)
	v_add_f32_e32 v98, v99, v100
	v_lshl_add_u64 v[104:105], s[2:3], 0, v[102:103]
	v_readlane_b32 s2, v251, 21
	v_readlane_b32 s3, v251, 22
	s_nop 1
	v_lshl_add_u64 v[102:103], s[2:3], 0, v[102:103]
	global_atomic_add_f32 v[102:103], v1, off
	global_atomic_add_f32 v[104:105], v98, off

; __device__ __forceinline__ float silu_f(float x) { return x * __builtin_amdgcn_rcpf(1.f + __expf(-x)); }
; __device__ __forceinline__ float gelu_f(float x) { const float u2 = 1.5957691216057308f * (x + 0.044715f * x * x * x); return x * __builtin_amdgcn_rcpf(1.f + __expf(-u2)); }
; __device__ __forceinline__ void atomic_add_agent(float* p, float v) { (void)__hip_atomic_fetch_add(p, v, __ATOMIC_RELAXED, __HIP_MEMORY_SCOPE_AGENT); }
; __device__ __forceinline__ v4u pack8(const float (&y)[8]) { return (v4u){pk2(y[0], y[1]), pk2(y[2], y[3]), pk2(y[4], y[5]), pk2(y[6], y[7])}; }
;     __device__ __forceinline__ void operator()(const f32x4 (&acc)[2][2][4][2], const pg8::Unit& u, int wr, int wc, int fr, int fq) const {
;     ...
;                         } else if (region == 1) {
; #pragma unroll
;                             for (int j = 0; j < 8; ++j) { y[j] = gelu_f(v[j]); s1 += y[j]; s2 += y[j] * y[j]; }
;                             *(v4u*)(o1 + off) = pack8(y);
;                         } else {
; #pragma unroll
;                             for (int j = 0; j < 8; ++j) y[j] = silu_f(v[j]);
;                             *(v4u*)(Y + off) = pack8(y);
;                         }
;                     }
;                     if (region == 1) {
;                         s1 += __shfl_xor(s1, 16); s1 += __shfl_xor(s1, 32); s2 += __shfl_xor(s2, 16); s2 += __shfl_xor(s2, 32);
;                         if (fq == 0) { atomic_add_agent(vs1 + row, s1); atomic_add_agent(vs2 + row, s2); }
;                     }
.LBB0_600:
	v_lshlrev_b64 v[86:87], 10, v[98:99]
	v_lshl_add_u64 v[86:87], v[86:87], 1, s[0:1]
	v_mov_b32_e32 v123, v0
	v_cvt_pk_bf16_f32 v82, v92, v93
	v_cvt_pk_bf16_f32 v83, v94, v95
	v_cvt_pk_bf16_f32 v84, v96, v97
	v_cvt_pk_bf16_f32 v85, v102, v103
	v_lshl_add_u64 v[86:87], v[86:87], 0, v[122:123]
	s_and_b64 vcc, exec, s[50:51]
	global_store_dwordx4 v[86:87], v[82:85], off offset:256
	s_cbranch_vccnz .LBB0_604
	s_nop 0
	v_and_b32_e32 v82, 64, v191
	v_xor_b32_e32 v1, 16, v191
	v_add_u32_e32 v82, 64, v82
	v_cmp_lt_i32_e32 vcc, v1, v82
	v_xor_b32_e32 v84, 32, v191
	s_nop 0
	v_cndmask_b32_e32 v1, v191, v1, vcc
	v_lshlrev_b32_e32 v83, 2, v1
	v_mov_b32_e32 v1, v101
	s_nop 1
	v_permlane16_swap_b32_e32 v1, v101
	v_mov_b32_e32 v83, v100
	s_nop 1
	v_permlane16_swap_b32_e32 v83, v100
	v_cmp_lt_i32_e32 vcc, v84, v82
	s_waitcnt lgkmcnt(1)
	v_add_f32_e32 v1, v101, v1
	v_cndmask_b32_e32 v82, v191, v84, vcc
	v_lshlrev_b32_e32 v84, 2, v82
	s_waitcnt lgkmcnt(0)
	v_add_f32_e32 v83, v100, v83
	v_mov_b32_e32 v82, v1
	s_nop 1
	v_permlane32_swap_b32_e32 v82, v1
	v_mov_b32_e32 v84, v83
	s_nop 1
	v_permlane32_swap_b32_e32 v84, v83
	s_and_saveexec_b64 s[0:1], s[42:43]
	s_cbranch_execz .LBB0_603
	v_readlane_b32 s2, v251, 23
	v_lshlrev_b64 v[86:87], 2, v[98:99]
	v_readlane_b32 s3, v251, 24
	s_waitcnt lgkmcnt(1)
	v_add_f32_e32 v1, v1, v82
	s_waitcnt lgkmcnt(0)
	v_add_f32_e32 v82, v83, v84
	v_lshl_add_u64 v[88:89], s[2:3], 0, v[86:87]
	v_readlane_b32 s2, v251, 21
	v_readlane_b32 s3, v251, 22
	s_nop 1
	v_lshl_add_u64 v[86:87], s[2:3], 0, v[86:87]
	global_atomic_add_f32 v[86:87], v1, off
	global_atomic_add_f32 v[88:89], v82, off

; __device__ __forceinline__ float silu_f(float x) { return x * __builtin_amdgcn_rcpf(1.f + __expf(-x)); }
; __device__ __forceinline__ float gelu_f(float x) { const float u2 = 1.5957691216057308f * (x + 0.044715f * x * x * x); return x * __builtin_amdgcn_rcpf(1.f + __expf(-u2)); }
; __device__ __forceinline__ void atomic_add_agent(float* p, float v) { (void)__hip_atomic_fetch_add(p, v, __ATOMIC_RELAXED, __HIP_MEMORY_SCOPE_AGENT); }
; __device__ __forceinline__ v4u pack8(const float (&y)[8]) { return (v4u){pk2(y[0], y[1]), pk2(y[2], y[3]), pk2(y[4], y[5]), pk2(y[6], y[7])}; }
;     __device__ __forceinline__ void operator()(const f32x4 (&acc)[2][2][4][2], const pg8::Unit& u, int wr, int wc, int fr, int fq) const {
;     ...
;                         } else if (region == 1) {
; #pragma unroll
;                             for (int j = 0; j < 8; ++j) { y[j] = gelu_f(v[j]); s1 += y[j]; s2 += y[j] * y[j]; }
;                             *(v4u*)(o1 + off) = pack8(y);
;                         } else {
; #pragma unroll
;                             for (int j = 0; j < 8; ++j) y[j] = silu_f(v[j]);
;                             *(v4u*)(Y + off) = pack8(y);
;                         }
;                     }
;                     if (region == 1) {
;                         s1 += __shfl_xor(s1, 16); s1 += __shfl_xor(s1, 32); s2 += __shfl_xor(s2, 16); s2 += __shfl_xor(s2, 32);
;                         if (fq == 0) { atomic_add_agent(vs1 + row, s1); atomic_add_agent(vs2 + row, s2); }
;                     }
.LBB0_619:
	v_lshlrev_b64 v[70:71], 10, v[82:83]
	v_lshl_add_u64 v[70:71], v[70:71], 1, s[0:1]
	v_mov_b32_e32 v123, v0
	v_cvt_pk_bf16_f32 v66, v76, v77
	v_cvt_pk_bf16_f32 v67, v78, v79
	v_cvt_pk_bf16_f32 v68, v80, v81
	v_cvt_pk_bf16_f32 v69, v86, v87
	v_lshl_add_u64 v[70:71], v[70:71], 0, v[122:123]
	s_and_b64 vcc, exec, s[50:51]
	global_store_dwordx4 v[70:71], v[66:69], off offset:256
	s_cbranch_vccnz .LBB0_623
	s_nop 0
	v_and_b32_e32 v66, 64, v191
	v_xor_b32_e32 v1, 16, v191
	v_add_u32_e32 v66, 64, v66
	v_cmp_lt_i32_e32 vcc, v1, v66
	v_xor_b32_e32 v68, 32, v191
	s_nop 0
	v_cndmask_b32_e32 v1, v191, v1, vcc
	v_lshlrev_b32_e32 v67, 2, v1
	v_mov_b32_e32 v1, v85
	s_nop 1
	v_permlane16_swap_b32_e32 v1, v85
	v_mov_b32_e32 v67, v84
	s_nop 1
	v_permlane16_swap_b32_e32 v67, v84
	v_cmp_lt_i32_e32 vcc, v68, v66
	s_waitcnt lgkmcnt(1)
	v_add_f32_e32 v1, v85, v1
	v_cndmask_b32_e32 v66, v191, v68, vcc
	v_lshlrev_b32_e32 v68, 2, v66
	s_waitcnt lgkmcnt(0)
	v_add_f32_e32 v67, v84, v67
	v_mov_b32_e32 v66, v1
	s_nop 1
	v_permlane32_swap_b32_e32 v66, v1
	v_mov_b32_e32 v68, v67
	s_nop 1
	v_permlane32_swap_b32_e32 v68, v67
	s_and_saveexec_b64 s[0:1], s[42:43]
	s_cbranch_execz .LBB0_622
	v_readlane_b32 s2, v251, 23
	v_lshlrev_b64 v[70:71], 2, v[82:83]
	v_readlane_b32 s3, v251, 24
	s_waitcnt lgkmcnt(1)
	v_add_f32_e32 v1, v1, v66
	s_waitcnt lgkmcnt(0)
	v_add_f32_e32 v66, v67, v68
	v_lshl_add_u64 v[72:73], s[2:3], 0, v[70:71]
	v_readlane_b32 s2, v251, 21
	v_readlane_b32 s3, v251, 22
	s_nop 1
	v_lshl_add_u64 v[70:71], s[2:3], 0, v[70:71]
	global_atomic_add_f32 v[70:71], v1, off
	global_atomic_add_f32 v[72:73], v66, off

; __device__ __forceinline__ float silu_f(float x) { return x * __builtin_amdgcn_rcpf(1.f + __expf(-x)); }
; __device__ __forceinline__ float gelu_f(float x) { const float u2 = 1.5957691216057308f * (x + 0.044715f * x * x * x); return x * __builtin_amdgcn_rcpf(1.f + __expf(-u2)); }
; __device__ __forceinline__ void atomic_add_agent(float* p, float v) { (void)__hip_atomic_fetch_add(p, v, __ATOMIC_RELAXED, __HIP_MEMORY_SCOPE_AGENT); }
; __device__ __forceinline__ v4u pack8(const float (&y)[8]) { return (v4u){pk2(y[0], y[1]), pk2(y[2], y[3]), pk2(y[4], y[5]), pk2(y[6], y[7])}; }
;     __device__ __forceinline__ void operator()(const f32x4 (&acc)[2][2][4][2], const pg8::Unit& u, int wr, int wc, int fr, int fq) const {
;     ...
;                         } else if (region == 1) {
; #pragma unroll
;                             for (int j = 0; j < 8; ++j) { y[j] = gelu_f(v[j]); s1 += y[j]; s2 += y[j] * y[j]; }
;                             *(v4u*)(o1 + off) = pack8(y);
;                         } else {
; #pragma unroll
;                             for (int j = 0; j < 8; ++j) y[j] = silu_f(v[j]);
;                             *(v4u*)(Y + off) = pack8(y);
;                         }
;                     }
;                     if (region == 1) {
;                         s1 += __shfl_xor(s1, 16); s1 += __shfl_xor(s1, 32); s2 += __shfl_xor(s2, 16); s2 += __shfl_xor(s2, 32);
;                         if (fq == 0) { atomic_add_agent(vs1 + row, s1); atomic_add_agent(vs2 + row, s2); }
;                     }
.LBB0_638:
	v_lshlrev_b64 v[54:55], 10, v[58:59]
	v_lshl_add_u64 v[54:55], v[54:55], 1, s[0:1]
	v_mov_b32_e32 v123, v0
	v_cvt_pk_bf16_f32 v50, v62, v63
	v_cvt_pk_bf16_f32 v51, v64, v65
	v_cvt_pk_bf16_f32 v52, v66, v67
	v_cvt_pk_bf16_f32 v53, v70, v71
	v_lshl_add_u64 v[54:55], v[54:55], 0, v[122:123]
	s_and_b64 vcc, exec, s[50:51]
	global_store_dwordx4 v[54:55], v[50:53], off offset:256
	s_cbranch_vccnz .LBB0_642
	s_nop 0
	v_and_b32_e32 v50, 64, v191
	v_xor_b32_e32 v1, 16, v191
	v_add_u32_e32 v50, 64, v50
	v_cmp_lt_i32_e32 vcc, v1, v50
	v_xor_b32_e32 v52, 32, v191
	s_nop 0
	v_cndmask_b32_e32 v1, v191, v1, vcc
	v_lshlrev_b32_e32 v51, 2, v1
	v_mov_b32_e32 v1, v69
	s_nop 1
	v_permlane16_swap_b32_e32 v1, v69
	v_mov_b32_e32 v51, v68
	s_nop 1
	v_permlane16_swap_b32_e32 v51, v68
	v_cmp_lt_i32_e32 vcc, v52, v50
	s_waitcnt lgkmcnt(1)
	v_add_f32_e32 v1, v69, v1
	v_cndmask_b32_e32 v50, v191, v52, vcc
	v_lshlrev_b32_e32 v52, 2, v50
	s_waitcnt lgkmcnt(0)
	v_add_f32_e32 v51, v68, v51
	v_mov_b32_e32 v50, v1
	s_nop 1
	v_permlane32_swap_b32_e32 v50, v1
	v_mov_b32_e32 v52, v51
	s_nop 1
	v_permlane32_swap_b32_e32 v52, v51
	s_and_saveexec_b64 s[0:1], s[42:43]
	s_cbranch_execz .LBB0_641
	v_readlane_b32 s2, v251, 23
	v_lshlrev_b64 v[54:55], 2, v[58:59]
	v_readlane_b32 s3, v251, 24
	s_waitcnt lgkmcnt(1)
	v_add_f32_e32 v1, v1, v50
	s_waitcnt lgkmcnt(0)
	v_add_f32_e32 v50, v51, v52
	v_lshl_add_u64 v[56:57], s[2:3], 0, v[54:55]
	v_readlane_b32 s2, v251, 21
	v_readlane_b32 s3, v251, 22
	s_nop 1
	v_lshl_add_u64 v[54:55], s[2:3], 0, v[54:55]
	global_atomic_add_f32 v[54:55], v1, off
	global_atomic_add_f32 v[56:57], v50, off

; __device__ __forceinline__ float silu_f(float x) { return x * __builtin_amdgcn_rcpf(1.f + __expf(-x)); }
; __device__ __forceinline__ float gelu_f(float x) { const float u2 = 1.5957691216057308f * (x + 0.044715f * x * x * x); return x * __builtin_amdgcn_rcpf(1.f + __expf(-u2)); }
; __device__ __forceinline__ void atomic_add_agent(float* p, float v) { (void)__hip_atomic_fetch_add(p, v, __ATOMIC_RELAXED, __HIP_MEMORY_SCOPE_AGENT); }
; __device__ __forceinline__ v4u pack8(const float (&y)[8]) { return (v4u){pk2(y[0], y[1]), pk2(y[2], y[3]), pk2(y[4], y[5]), pk2(y[6], y[7])}; }
;     __device__ __forceinline__ void operator()(const f32x4 (&acc)[2][2][4][2], const pg8::Unit& u, int wr, int wc, int fr, int fq) const {
;     ...
;                         } else if (region == 1) {
; #pragma unroll
;                             for (int j = 0; j < 8; ++j) { y[j] = gelu_f(v[j]); s1 += y[j]; s2 += y[j] * y[j]; }
;                             *(v4u*)(o1 + off) = pack8(y);
;                         } else {
; #pragma unroll
;                             for (int j = 0; j < 8; ++j) y[j] = silu_f(v[j]);
;                             *(v4u*)(Y + off) = pack8(y);
;                         }
;                     }
;                     if (region == 1) {
;                         s1 += __shfl_xor(s1, 16); s1 += __shfl_xor(s1, 32); s2 += __shfl_xor(s2, 16); s2 += __shfl_xor(s2, 32);
;                         if (fq == 0) { atomic_add_agent(vs1 + row, s1); atomic_add_agent(vs2 + row, s2); }
;                     }
.LBB0_657:
	v_lshlrev_b64 v[38:39], 10, v[42:43]
	v_lshl_add_u64 v[38:39], v[38:39], 1, s[0:1]
	v_mov_b32_e32 v123, v0
	v_cvt_pk_bf16_f32 v34, v46, v47
	v_cvt_pk_bf16_f32 v35, v48, v49
	v_cvt_pk_bf16_f32 v36, v50, v51
	v_cvt_pk_bf16_f32 v37, v54, v55
	v_lshl_add_u64 v[38:39], v[38:39], 0, v[122:123]
	s_and_b64 vcc, exec, s[50:51]
	global_store_dwordx4 v[38:39], v[34:37], off offset:256
	s_cbranch_vccnz .LBB0_661
	s_nop 0
	v_and_b32_e32 v34, 64, v191
	v_xor_b32_e32 v1, 16, v191
	v_add_u32_e32 v34, 64, v34
	v_cmp_lt_i32_e32 vcc, v1, v34
	v_xor_b32_e32 v36, 32, v191
	s_nop 0
	v_cndmask_b32_e32 v1, v191, v1, vcc
	v_lshlrev_b32_e32 v35, 2, v1
	v_mov_b32_e32 v1, v53
	s_nop 1
	v_permlane16_swap_b32_e32 v1, v53
	v_mov_b32_e32 v35, v52
	s_nop 1
	v_permlane16_swap_b32_e32 v35, v52
	v_cmp_lt_i32_e32 vcc, v36, v34
	s_waitcnt lgkmcnt(1)
	v_add_f32_e32 v1, v53, v1
	v_cndmask_b32_e32 v34, v191, v36, vcc
	v_lshlrev_b32_e32 v36, 2, v34
	s_waitcnt lgkmcnt(0)
	v_add_f32_e32 v35, v52, v35
	v_mov_b32_e32 v34, v1
	s_nop 1
	v_permlane32_swap_b32_e32 v34, v1
	v_mov_b32_e32 v36, v35
	s_nop 1
	v_permlane32_swap_b32_e32 v36, v35
	s_and_saveexec_b64 s[0:1], s[42:43]
	s_cbranch_execz .LBB0_660
	v_readlane_b32 s2, v251, 23
	v_lshlrev_b64 v[38:39], 2, v[42:43]
	v_readlane_b32 s3, v251, 24
	s_waitcnt lgkmcnt(1)
	v_add_f32_e32 v1, v1, v34
	s_waitcnt lgkmcnt(0)
	v_add_f32_e32 v34, v35, v36
	v_lshl_add_u64 v[40:41], s[2:3], 0, v[38:39]
	v_readlane_b32 s2, v251, 21
	v_readlane_b32 s3, v251, 22
	s_nop 1
	v_lshl_add_u64 v[38:39], s[2:3], 0, v[38:39]
	global_atomic_add_f32 v[38:39], v1, off
	global_atomic_add_f32 v[40:41], v34, off

; __device__ __forceinline__ float silu_f(float x) { return x * __builtin_amdgcn_rcpf(1.f + __expf(-x)); }
; __device__ __forceinline__ float gelu_f(float x) { const float u2 = 1.5957691216057308f * (x + 0.044715f * x * x * x); return x * __builtin_amdgcn_rcpf(1.f + __expf(-u2)); }
; __device__ __forceinline__ void atomic_add_agent(float* p, float v) { (void)__hip_atomic_fetch_add(p, v, __ATOMIC_RELAXED, __HIP_MEMORY_SCOPE_AGENT); }
; __device__ __forceinline__ v4u pack8(const float (&y)[8]) { return (v4u){pk2(y[0], y[1]), pk2(y[2], y[3]), pk2(y[4], y[5]), pk2(y[6], y[7])}; }
;     __device__ __forceinline__ void operator()(const f32x4 (&acc)[2][2][4][2], const pg8::Unit& u, int wr, int wc, int fr, int fq) const {
;     ...
;                         } else if (region == 1) {
; #pragma unroll
;                             for (int j = 0; j < 8; ++j) { y[j] = gelu_f(v[j]); s1 += y[j]; s2 += y[j] * y[j]; }
;                             *(v4u*)(o1 + off) = pack8(y);
;                         } else {
; #pragma unroll
;                             for (int j = 0; j < 8; ++j) y[j] = silu_f(v[j]);
;                             *(v4u*)(Y + off) = pack8(y);
;                         }
;                     }
;                     if (region == 1) {
;                         s1 += __shfl_xor(s1, 16); s1 += __shfl_xor(s1, 32); s2 += __shfl_xor(s2, 16); s2 += __shfl_xor(s2, 32);
;                         if (fq == 0) { atomic_add_agent(vs1 + row, s1); atomic_add_agent(vs2 + row, s2); }
;                     }
.LBB0_676:
	v_lshlrev_b64 v[22:23], 10, v[26:27]
	v_lshl_add_u64 v[22:23], v[22:23], 1, s[0:1]
	v_mov_b32_e32 v123, v0
	v_cvt_pk_bf16_f32 v18, v30, v31
	v_cvt_pk_bf16_f32 v19, v32, v33
	v_cvt_pk_bf16_f32 v20, v34, v35
	v_cvt_pk_bf16_f32 v21, v38, v39
	v_lshl_add_u64 v[22:23], v[22:23], 0, v[122:123]
	s_and_b64 vcc, exec, s[50:51]
	global_store_dwordx4 v[22:23], v[18:21], off offset:256
	s_cbranch_vccnz .LBB0_680
	s_nop 0
	v_and_b32_e32 v18, 64, v191
	v_xor_b32_e32 v1, 16, v191
	v_add_u32_e32 v18, 64, v18
	v_cmp_lt_i32_e32 vcc, v1, v18
	v_xor_b32_e32 v20, 32, v191
	s_nop 0
	v_cndmask_b32_e32 v1, v191, v1, vcc
	v_lshlrev_b32_e32 v19, 2, v1
	v_mov_b32_e32 v1, v37
	s_nop 1
	v_permlane16_swap_b32_e32 v1, v37
	v_mov_b32_e32 v19, v36
	s_nop 1
	v_permlane16_swap_b32_e32 v19, v36
	v_cmp_lt_i32_e32 vcc, v20, v18
	s_waitcnt lgkmcnt(1)
	v_add_f32_e32 v1, v37, v1
	v_cndmask_b32_e32 v18, v191, v20, vcc
	v_lshlrev_b32_e32 v20, 2, v18
	s_waitcnt lgkmcnt(0)
	v_add_f32_e32 v19, v36, v19
	v_mov_b32_e32 v18, v1
	s_nop 1
	v_permlane32_swap_b32_e32 v18, v1
	v_mov_b32_e32 v20, v19
	s_nop 1
	v_permlane32_swap_b32_e32 v20, v19
	s_and_saveexec_b64 s[0:1], s[42:43]
	s_cbranch_execz .LBB0_679
	v_readlane_b32 s2, v251, 23
	v_lshlrev_b64 v[22:23], 2, v[26:27]
	v_readlane_b32 s3, v251, 24
	s_waitcnt lgkmcnt(1)
	v_add_f32_e32 v1, v1, v18
	s_waitcnt lgkmcnt(0)
	v_add_f32_e32 v18, v19, v20
	v_lshl_add_u64 v[24:25], s[2:3], 0, v[22:23]
	v_readlane_b32 s2, v251, 21
	v_readlane_b32 s3, v251, 22
	s_nop 1
	v_lshl_add_u64 v[22:23], s[2:3], 0, v[22:23]
	global_atomic_add_f32 v[22:23], v1, off
	global_atomic_add_f32 v[24:25], v18, off

; __device__ __forceinline__ float silu_f(float x) { return x * __builtin_amdgcn_rcpf(1.f + __expf(-x)); }
; __device__ __forceinline__ float gelu_f(float x) { const float u2 = 1.5957691216057308f * (x + 0.044715f * x * x * x); return x * __builtin_amdgcn_rcpf(1.f + __expf(-u2)); }
; __device__ __forceinline__ void atomic_add_agent(float* p, float v) { (void)__hip_atomic_fetch_add(p, v, __ATOMIC_RELAXED, __HIP_MEMORY_SCOPE_AGENT); }
; __device__ __forceinline__ v4u pack8(const float (&y)[8]) { return (v4u){pk2(y[0], y[1]), pk2(y[2], y[3]), pk2(y[4], y[5]), pk2(y[6], y[7])}; }
;     __device__ __forceinline__ void operator()(const f32x4 (&acc)[2][2][4][2], const pg8::Unit& u, int wr, int wc, int fr, int fq) const {
;     ...
;                         } else if (region == 1) {
; #pragma unroll
;                             for (int j = 0; j < 8; ++j) { y[j] = gelu_f(v[j]); s1 += y[j]; s2 += y[j] * y[j]; }
;                             *(v4u*)(o1 + off) = pack8(y);
;                         } else {
; #pragma unroll
;                             for (int j = 0; j < 8; ++j) y[j] = silu_f(v[j]);
;                             *(v4u*)(Y + off) = pack8(y);
;                         }
;                     }
;                     if (region == 1) {
;                         s1 += __shfl_xor(s1, 16); s1 += __shfl_xor(s1, 32); s2 += __shfl_xor(s2, 16); s2 += __shfl_xor(s2, 32);
;                         if (fq == 0) { atomic_add_agent(vs1 + row, s1); atomic_add_agent(vs2 + row, s2); }
;                     }
.LBB0_695:
	v_lshlrev_b64 v[6:7], 10, v[10:11]
	v_lshl_add_u64 v[6:7], v[6:7], 1, s[0:1]
	v_mov_b32_e32 v123, v0
	s_and_b64 vcc, exec, s[50:51]
	v_readlane_b32 s50, v255, 24
	v_cvt_pk_bf16_f32 v2, v14, v15
	v_cvt_pk_bf16_f32 v3, v16, v17
	v_cvt_pk_bf16_f32 v4, v18, v19
	v_cvt_pk_bf16_f32 v5, v22, v23
	v_lshl_add_u64 v[6:7], v[6:7], 0, v[122:123]
	v_readlane_b32 s51, v255, 25
	global_store_dwordx4 v[6:7], v[2:5], off offset:256
	s_cbranch_vccnz .LBB0_699
	s_nop 0
	v_and_b32_e32 v2, 64, v191
	v_xor_b32_e32 v1, 16, v191
	v_add_u32_e32 v2, 64, v2
	v_cmp_lt_i32_e32 vcc, v1, v2
	v_xor_b32_e32 v4, 32, v191
	s_nop 0
	v_cndmask_b32_e32 v1, v191, v1, vcc
	v_lshlrev_b32_e32 v3, 2, v1
	v_mov_b32_e32 v1, v21
	s_nop 1
	v_permlane16_swap_b32_e32 v1, v21
	v_mov_b32_e32 v3, v20
	s_nop 1
	v_permlane16_swap_b32_e32 v3, v20
	v_cmp_lt_i32_e32 vcc, v4, v2
	s_waitcnt lgkmcnt(1)
	v_add_f32_e32 v1, v21, v1
	v_cndmask_b32_e32 v2, v191, v4, vcc
	v_lshlrev_b32_e32 v4, 2, v2
	s_waitcnt lgkmcnt(0)
	v_add_f32_e32 v3, v20, v3
	v_mov_b32_e32 v2, v1
	s_nop 1
	v_permlane32_swap_b32_e32 v2, v1
	v_mov_b32_e32 v4, v3
	s_nop 1
	v_permlane32_swap_b32_e32 v4, v3
	s_and_saveexec_b64 s[0:1], s[42:43]
	s_cbranch_execz .LBB0_698
	v_readlane_b32 s2, v251, 23
	v_lshlrev_b64 v[6:7], 2, v[10:11]
	v_readlane_b32 s3, v251, 24
	s_waitcnt lgkmcnt(1)
	v_add_f32_e32 v1, v1, v2
	s_waitcnt lgkmcnt(0)
	v_add_f32_e32 v2, v3, v4
	v_lshl_add_u64 v[8:9], s[2:3], 0, v[6:7]
	v_readlane_b32 s2, v251, 21
	v_readlane_b32 s3, v251, 22
	s_nop 1
	v_lshl_add_u64 v[6:7], s[2:3], 0, v[6:7]
	global_atomic_add_f32 v[6:7], v1, off
	global_atomic_add_f32 v[8:9], v2, off

; __device__ __forceinline__ float bflo(unsigned u) { return __uint_as_float(u << 16); }
; __device__ __forceinline__ float bfhi(unsigned u) { return __uint_as_float(u & 0xffff0000u); }
; __device__ __forceinline__ unsigned pk2(float lo, float hi) { f32x2_t v = {lo, hi}; bf16x2_t b = __builtin_convertvector(v, bf16x2_t); return __builtin_bit_cast(unsigned, b); }
; __device__ __forceinline__ void atomic_add_agent(float* p, float v) { (void)__hip_atomic_fetch_add(p, v, __ATOMIC_RELAXED, __HIP_MEMORY_SCOPE_AGENT); }
;     __device__ __forceinline__ void operator()(const f32x4 (&acc)[2][2][4][2], const pg8::Unit& u, int wr, int wc, int fr, int fq) const {
;     ...
;                 const int row = row0 + ai * 128 + m * 16; float s2 = 0.f;
; #pragma unroll
;                 for (int bj = 0; bj < 2; ++bj) {
;                     const size_t off = (size_t)row * 1024 + c0 + bj * 128;
;                     f32x4 x0, x1;
;                     if (xin) { x0 = *(const f32x4*)(xin + off); x1 = *(const f32x4*)(xin + off + 4); }
;                     else { const v4u xv = *(const v4u*)(xb + off); x0 = (f32x4){bflo(xv.x), bfhi(xv.x), bflo(xv.y), bfhi(xv.y)}; x1 = (f32x4){bflo(xv.z), bfhi(xv.z), bflo(xv.w), bfhi(xv.w)}; }
;                     const f32x4 n0 = x0 + acc[ai][bj][m][0], n1 = x1 + acc[ai][bj][m][1];
;                     if (xout) { *(f32x4*)(xout + off) = n0; *(f32x4*)(xout + off + 4) = n1; }
;                     else *(v4u*)(xb + off) = (v4u){pk2(n0[0], n0[1]), pk2(n0[2], n0[3]), pk2(n1[0], n1[1]), pk2(n1[2], n1[3])};
;                     s2 += ((n0[0] * n0[0] + n0[1] * n0[1]) + (n0[2] * n0[2] + n0[3] * n0[3])) + ((n1[0] * n1[0] + n1[1] * n1[1]) + (n1[2] * n1[2] + n1[3] * n1[3]));
;                 }
;                 if (ssq) { s2 += __shfl_xor(s2, 16); s2 += __shfl_xor(s2, 32); if (fq == 0) atomic_add_agent(ssq + row, s2); }
.LBB0_831:
	v_lshl_add_u32 v168, s38, 8, v1
	v_lshl_or_b32 v166, s37, 8, v170
	v_ashrrev_i32_e32 v169, 31, v168
	v_ashrrev_i32_e32 v167, 31, v166
	v_lshlrev_b64 v[150:151], 10, v[168:169]
	v_lshl_add_u64 v[150:151], v[150:151], 0, v[166:167]
	v_lshl_add_u64 v[154:155], v[150:151], 1, s[54:55]
	v_mov_b32_e32 v150, v124
	v_mov_b32_e32 v151, v125
	v_mov_b32_e32 v152, v122
	v_mov_b32_e32 v153, v123
	v_cvt_pk_bf16_f32 v122, v126, v127
	v_cvt_pk_bf16_f32 v123, v128, v129
	v_cvt_pk_bf16_f32 v124, v152, v153
	v_cvt_pk_bf16_f32 v125, v150, v151
	global_store_dwordx4 v[154:155], v[122:125], off
	s_nop 1
	v_mul_f32_e32 v122, v127, v127
	v_mul_f32_e32 v123, v129, v129
	v_fmac_f32_e32 v122, v126, v126
	v_fmac_f32_e32 v123, v128, v128
	v_add_f32_e32 v122, v122, v123
	v_mul_f32_e32 v123, v153, v153
	v_mul_f32_e32 v124, v151, v151
	v_fmac_f32_e32 v123, v152, v152
	v_fmac_f32_e32 v124, v150, v150
	v_add_f32_e32 v123, v123, v124
	v_add_f32_e32 v150, v122, v123
	v_mov_b32_e32 v122, v116
	v_mov_b32_e32 v123, v117
	v_mov_b32_e32 v124, v114
	v_mov_b32_e32 v125, v115
	v_cvt_pk_bf16_f32 v114, v118, v119
	v_cvt_pk_bf16_f32 v115, v120, v121
	v_cvt_pk_bf16_f32 v116, v124, v125
	v_cvt_pk_bf16_f32 v117, v122, v123
	global_store_dwordx4 v[154:155], v[114:117], off offset:256
	s_nop 1
	v_mul_f32_e32 v114, v119, v119
	v_mul_f32_e32 v115, v121, v121
	v_fmac_f32_e32 v114, v118, v118
	v_fmac_f32_e32 v115, v120, v120
	v_add_f32_e32 v114, v114, v115
	v_mul_f32_e32 v115, v125, v125
	v_mul_f32_e32 v116, v123, v123
	v_fmac_f32_e32 v115, v124, v124
	v_fmac_f32_e32 v116, v122, v122
	v_add_f32_e32 v115, v115, v116
	v_and_b32_e32 v116, 64, v191
	v_add_f32_e32 v114, v114, v115
	v_xor_b32_e32 v115, 16, v191
	v_add_u32_e32 v117, 64, v116
	v_cmp_lt_i32_e32 vcc, v115, v117
	v_add_f32_e32 v114, v150, v114
	s_nop 0
	v_cndmask_b32_e32 v115, v191, v115, vcc
	v_lshlrev_b32_e32 v116, 2, v115
	v_mov_b32_e32 v115, v114
	s_nop 1
	v_permlane16_swap_b32_e32 v115, v114
	s_waitcnt lgkmcnt(0)
	v_add_f32_e32 v114, v114, v115
	v_xor_b32_e32 v115, 32, v191
	v_cmp_lt_i32_e32 vcc, v115, v117
	s_nop 1
	v_cndmask_b32_e32 v115, v191, v115, vcc
	v_lshlrev_b32_e32 v117, 2, v115
	v_mov_b32_e32 v115, v114
	s_nop 1
	v_permlane32_swap_b32_e32 v115, v114
	s_and_saveexec_b64 s[2:3], s[0:1]
	s_cbranch_execz .LBB0_833
	v_readlane_b32 s20, v253, 11
	v_readlane_b32 s21, v253, 12
	s_waitcnt lgkmcnt(0)
	v_add_f32_e32 v114, v114, v115
	v_lshl_add_u64 v[118:119], v[168:169], 2, s[20:21]
	global_atomic_add_f32 v[118:119], v114, off
.LBB0_833:
	s_or_b64 exec, exec, s[2:3]
	v_or_b32_e32 v114, 16, v168
	s_waitcnt lgkmcnt(0)
	v_ashrrev_i32_e32 v115, 31, v114
	v_lshlrev_b64 v[118:119], 10, v[114:115]
	v_lshl_add_u64 v[118:119], v[118:119], 0, v[166:167]
	v_lshl_add_u64 v[122:123], v[118:119], 1, s[54:55]
	v_mov_b32_e32 v118, v108
	v_mov_b32_e32 v119, v109
	v_mov_b32_e32 v120, v106
	v_mov_b32_e32 v121, v107
	v_cvt_pk_bf16_f32 v106, v110, v111
	v_cvt_pk_bf16_f32 v107, v112, v113
	v_cvt_pk_bf16_f32 v108, v120, v121
	v_cvt_pk_bf16_f32 v109, v118, v119
	global_store_dwordx4 v[122:123], v[106:109], off
	s_nop 1
	v_mul_f32_e32 v106, v111, v111
	v_mul_f32_e32 v107, v113, v113
	v_fmac_f32_e32 v106, v110, v110
	v_fmac_f32_e32 v107, v112, v112
	v_add_f32_e32 v106, v106, v107
	v_mul_f32_e32 v107, v121, v121
	v_mul_f32_e32 v108, v119, v119
	v_fmac_f32_e32 v107, v120, v120
	v_fmac_f32_e32 v108, v118, v118
	v_add_f32_e32 v107, v107, v108
	v_add_f32_e32 v118, v106, v107
	v_mov_b32_e32 v106, v100
	v_mov_b32_e32 v107, v101
	v_mov_b32_e32 v108, v98
	v_mov_b32_e32 v109, v99
	v_cvt_pk_bf16_f32 v98, v102, v103
	v_cvt_pk_bf16_f32 v99, v104, v105
	v_cvt_pk_bf16_f32 v100, v108, v109
	v_cvt_pk_bf16_f32 v101, v106, v107
	global_store_dwordx4 v[122:123], v[98:101], off offset:256
	s_nop 1
	v_mul_f32_e32 v98, v103, v103
	v_mul_f32_e32 v99, v105, v105
	v_fmac_f32_e32 v98, v102, v102
	v_fmac_f32_e32 v99, v104, v104
	v_add_f32_e32 v98, v98, v99
	v_mul_f32_e32 v99, v109, v109
	v_mul_f32_e32 v100, v107, v107
	v_fmac_f32_e32 v99, v108, v108
	v_fmac_f32_e32 v100, v106, v106
	v_add_f32_e32 v99, v99, v100
	v_add_f32_e32 v98, v98, v99
	v_add_f32_e32 v98, v118, v98
	v_mov_b32_e32 v99, v98
	s_nop 1
	v_permlane16_swap_b32_e32 v99, v98
	s_waitcnt lgkmcnt(0)
	v_add_f32_e32 v98, v98, v99
	v_mov_b32_e32 v99, v98
	s_nop 1
	v_permlane32_swap_b32_e32 v99, v98
	s_and_saveexec_b64 s[2:3], s[0:1]
	s_cbranch_execz .LBB0_835
	v_readlane_b32 s20, v253, 11
	v_readlane_b32 s21, v253, 12
	s_waitcnt lgkmcnt(0)
	v_add_f32_e32 v98, v98, v99
	v_lshl_add_u64 v[100:101], v[114:115], 2, s[20:21]
	global_atomic_add_f32 v[100:101], v98, off
.LBB0_835:
	s_or_b64 exec, exec, s[2:3]
	v_or_b32_e32 v98, 32, v168
	s_waitcnt lgkmcnt(0)
	v_ashrrev_i32_e32 v99, 31, v98
	v_lshlrev_b64 v[100:101], 10, v[98:99]
	v_lshl_add_u64 v[100:101], v[100:101], 0, v[166:167]
	v_lshl_add_u64 v[104:105], v[100:101], 1, s[54:55]
	v_mov_b32_e32 v100, v92
	v_mov_b32_e32 v101, v93
	v_mov_b32_e32 v102, v90
	v_mov_b32_e32 v103, v91
	v_cvt_pk_bf16_f32 v90, v94, v95
	v_cvt_pk_bf16_f32 v91, v96, v97
	v_cvt_pk_bf16_f32 v92, v102, v103
	v_cvt_pk_bf16_f32 v93, v100, v101
	global_store_dwordx4 v[104:105], v[90:93], off
	s_nop 1
	v_mul_f32_e32 v90, v95, v95
	v_mul_f32_e32 v91, v97, v97
	v_fmac_f32_e32 v90, v94, v94
	v_fmac_f32_e32 v91, v96, v96
	v_add_f32_e32 v90, v90, v91
	v_mul_f32_e32 v91, v103, v103
	v_mul_f32_e32 v92, v101, v101
	v_fmac_f32_e32 v91, v102, v102
	v_fmac_f32_e32 v92, v100, v100
	v_add_f32_e32 v91, v91, v92
	v_add_f32_e32 v100, v90, v91
	v_mov_b32_e32 v90, v84
	v_mov_b32_e32 v91, v85
	v_mov_b32_e32 v92, v82
	v_mov_b32_e32 v93, v83
	v_cvt_pk_bf16_f32 v82, v86, v87
	v_cvt_pk_bf16_f32 v83, v88, v89
	v_cvt_pk_bf16_f32 v84, v92, v93
	v_cvt_pk_bf16_f32 v85, v90, v91
	global_store_dwordx4 v[104:105], v[82:85], off offset:256
	s_nop 1
	v_mul_f32_e32 v82, v87, v87
	v_mul_f32_e32 v83, v89, v89
	v_fmac_f32_e32 v82, v86, v86
	v_fmac_f32_e32 v83, v88, v88
	v_add_f32_e32 v82, v82, v83
	v_mul_f32_e32 v83, v93, v93
	v_mul_f32_e32 v84, v91, v91
	v_fmac_f32_e32 v83, v92, v92
	v_fmac_f32_e32 v84, v90, v90
	v_add_f32_e32 v83, v83, v84
	v_add_f32_e32 v82, v82, v83
	v_add_f32_e32 v82, v100, v82
	v_mov_b32_e32 v83, v82
	s_nop 1
	v_permlane16_swap_b32_e32 v83, v82
	s_waitcnt lgkmcnt(0)
	v_add_f32_e32 v82, v82, v83
	v_mov_b32_e32 v83, v82
	s_nop 1
	v_permlane32_swap_b32_e32 v83, v82
	s_and_saveexec_b64 s[2:3], s[0:1]
	s_cbranch_execz .LBB0_837
	v_readlane_b32 s20, v253, 11
	v_readlane_b32 s21, v253, 12
	s_waitcnt lgkmcnt(0)
	v_add_f32_e32 v82, v82, v83
	v_lshl_add_u64 v[84:85], v[98:99], 2, s[20:21]
	global_atomic_add_f32 v[84:85], v82, off
; __device__ __forceinline__ float bflo(unsigned u) { return __uint_as_float(u << 16); }
; __device__ __forceinline__ float bfhi(unsigned u) { return __uint_as_float(u & 0xffff0000u); }
; __device__ __forceinline__ unsigned pk2(float lo, float hi) { f32x2_t v = {lo, hi}; bf16x2_t b = __builtin_convertvector(v, bf16x2_t); return __builtin_bit_cast(unsigned, b); }
; __device__ __forceinline__ void atomic_add_agent(float* p, float v) { (void)__hip_atomic_fetch_add(p, v, __ATOMIC_RELAXED, __HIP_MEMORY_SCOPE_AGENT); }
;     __device__ __forceinline__ void operator()(const f32x4 (&acc)[2][2][4][2], const pg8::Unit& u, int wr, int wc, int fr, int fq) const {
;     ...
;                 const int row = row0 + ai * 128 + m * 16; float s2 = 0.f;
; #pragma unroll
;                 for (int bj = 0; bj < 2; ++bj) {
;                     const size_t off = (size_t)row * 1024 + c0 + bj * 128;
;                     f32x4 x0, x1;
;                     if (xin) { x0 = *(const f32x4*)(xin + off); x1 = *(const f32x4*)(xin + off + 4); }
;                     else { const v4u xv = *(const v4u*)(xb + off); x0 = (f32x4){bflo(xv.x), bfhi(xv.x), bflo(xv.y), bfhi(xv.y)}; x1 = (f32x4){bflo(xv.z), bfhi(xv.z), bflo(xv.w), bfhi(xv.w)}; }
;                     const f32x4 n0 = x0 + acc[ai][bj][m][0], n1 = x1 + acc[ai][bj][m][1];
;                     if (xout) { *(f32x4*)(xout + off) = n0; *(f32x4*)(xout + off + 4) = n1; }
;                     else *(v4u*)(xb + off) = (v4u){pk2(n0[0], n0[1]), pk2(n0[2], n0[3]), pk2(n1[0], n1[1]), pk2(n1[2], n1[3])};
;                     s2 += ((n0[0] * n0[0] + n0[1] * n0[1]) + (n0[2] * n0[2] + n0[3] * n0[3])) + ((n1[0] * n1[0] + n1[1] * n1[1]) + (n1[2] * n1[2] + n1[3] * n1[3]));
;                 }
;                 if (ssq) { s2 += __shfl_xor(s2, 16); s2 += __shfl_xor(s2, 32); if (fq == 0) atomic_add_agent(ssq + row, s2); }
.LBB0_837:
	s_or_b64 exec, exec, s[2:3]
	v_or_b32_e32 v82, 48, v168
	s_waitcnt lgkmcnt(0)
	v_ashrrev_i32_e32 v83, 31, v82
	v_lshlrev_b64 v[84:85], 10, v[82:83]
	v_lshl_add_u64 v[84:85], v[84:85], 0, v[166:167]
	v_lshl_add_u64 v[88:89], v[84:85], 1, s[54:55]
	v_mov_b32_e32 v84, v76
	v_mov_b32_e32 v85, v77
	v_mov_b32_e32 v86, v74
	v_mov_b32_e32 v87, v75
	v_cvt_pk_bf16_f32 v74, v78, v79
	v_cvt_pk_bf16_f32 v75, v80, v81
	v_cvt_pk_bf16_f32 v76, v86, v87
	v_cvt_pk_bf16_f32 v77, v84, v85
	global_store_dwordx4 v[88:89], v[74:77], off
	s_nop 1
	v_mul_f32_e32 v74, v79, v79
	v_mul_f32_e32 v75, v81, v81
	v_fmac_f32_e32 v74, v78, v78
	v_fmac_f32_e32 v75, v80, v80
	v_add_f32_e32 v74, v74, v75
	v_mul_f32_e32 v75, v87, v87
	v_mul_f32_e32 v76, v85, v85
	v_fmac_f32_e32 v75, v86, v86
	v_fmac_f32_e32 v76, v84, v84
	v_add_f32_e32 v75, v75, v76
	v_add_f32_e32 v84, v74, v75
	v_mov_b32_e32 v74, v68
	v_mov_b32_e32 v75, v69
	v_mov_b32_e32 v76, v66
	v_mov_b32_e32 v77, v67
	v_cvt_pk_bf16_f32 v66, v70, v71
	v_cvt_pk_bf16_f32 v67, v72, v73
	v_cvt_pk_bf16_f32 v68, v76, v77
	v_cvt_pk_bf16_f32 v69, v74, v75
	global_store_dwordx4 v[88:89], v[66:69], off offset:256
	s_nop 1
	v_mul_f32_e32 v66, v71, v71
	v_mul_f32_e32 v67, v73, v73
	v_fmac_f32_e32 v66, v70, v70
	v_fmac_f32_e32 v67, v72, v72
	v_add_f32_e32 v66, v66, v67
	v_mul_f32_e32 v67, v77, v77
	v_mul_f32_e32 v68, v75, v75
	v_fmac_f32_e32 v67, v76, v76
	v_fmac_f32_e32 v68, v74, v74
	v_add_f32_e32 v67, v67, v68
	v_add_f32_e32 v66, v66, v67
	v_add_f32_e32 v66, v84, v66
	v_mov_b32_e32 v67, v66
	s_nop 1
	v_permlane16_swap_b32_e32 v67, v66
	s_waitcnt lgkmcnt(0)
	v_add_f32_e32 v66, v66, v67
	v_mov_b32_e32 v67, v66
	s_nop 1
	v_permlane32_swap_b32_e32 v67, v66
	s_and_saveexec_b64 s[2:3], s[0:1]
	s_cbranch_execz .LBB0_839
	v_readlane_b32 s20, v253, 11
	v_readlane_b32 s21, v253, 12
	s_waitcnt lgkmcnt(0)
	v_add_f32_e32 v66, v66, v67
	v_lshl_add_u64 v[68:69], v[82:83], 2, s[20:21]
	global_atomic_add_f32 v[68:69], v66, off
.LBB0_839:
	s_or_b64 exec, exec, s[2:3]
	v_add_u32_e32 v66, 0x80, v168
	s_waitcnt lgkmcnt(0)
	v_ashrrev_i32_e32 v67, 31, v66
	v_lshlrev_b64 v[68:69], 10, v[66:67]
	v_lshl_add_u64 v[68:69], v[68:69], 0, v[166:167]
	v_lshl_add_u64 v[72:73], v[68:69], 1, s[54:55]
	v_mov_b32_e32 v68, v60
	v_mov_b32_e32 v69, v61
	v_mov_b32_e32 v70, v58
	v_mov_b32_e32 v71, v59
	v_cvt_pk_bf16_f32 v58, v62, v63
	v_cvt_pk_bf16_f32 v59, v64, v65
	v_cvt_pk_bf16_f32 v60, v70, v71
	v_cvt_pk_bf16_f32 v61, v68, v69
	global_store_dwordx4 v[72:73], v[58:61], off
	s_nop 1
	v_mul_f32_e32 v58, v63, v63
	v_mul_f32_e32 v59, v65, v65
	v_fmac_f32_e32 v58, v62, v62
	v_fmac_f32_e32 v59, v64, v64
	v_add_f32_e32 v58, v58, v59
	v_mul_f32_e32 v59, v71, v71
	v_mul_f32_e32 v60, v69, v69
	v_fmac_f32_e32 v59, v70, v70
	v_fmac_f32_e32 v60, v68, v68
	v_add_f32_e32 v59, v59, v60
	v_add_f32_e32 v68, v58, v59
	v_mov_b32_e32 v58, v52
	v_mov_b32_e32 v59, v53
	v_mov_b32_e32 v60, v50
	v_mov_b32_e32 v61, v51
	v_cvt_pk_bf16_f32 v50, v54, v55
	v_cvt_pk_bf16_f32 v51, v56, v57
	v_cvt_pk_bf16_f32 v52, v60, v61
	v_cvt_pk_bf16_f32 v53, v58, v59
	global_store_dwordx4 v[72:73], v[50:53], off offset:256
	s_nop 1
	v_mul_f32_e32 v50, v55, v55
	v_mul_f32_e32 v51, v57, v57
	v_fmac_f32_e32 v50, v54, v54
	v_fmac_f32_e32 v51, v56, v56
	v_add_f32_e32 v50, v50, v51
	v_mul_f32_e32 v51, v61, v61
	v_mul_f32_e32 v52, v59, v59
	v_fmac_f32_e32 v51, v60, v60
	v_fmac_f32_e32 v52, v58, v58
	v_add_f32_e32 v51, v51, v52
	v_add_f32_e32 v50, v50, v51
	v_add_f32_e32 v50, v68, v50
	v_mov_b32_e32 v51, v50
	s_nop 1
	v_permlane16_swap_b32_e32 v51, v50
	s_waitcnt lgkmcnt(0)
	v_add_f32_e32 v50, v50, v51
	v_mov_b32_e32 v51, v50
	s_nop 1
	v_permlane32_swap_b32_e32 v51, v50
	s_and_saveexec_b64 s[2:3], s[0:1]
	s_cbranch_execz .LBB0_841
	v_readlane_b32 s20, v253, 11
	v_readlane_b32 s21, v253, 12
	s_waitcnt lgkmcnt(0)
	v_add_f32_e32 v50, v50, v51
	v_lshl_add_u64 v[52:53], v[66:67], 2, s[20:21]
	global_atomic_add_f32 v[52:53], v50, off
; __device__ __forceinline__ float bflo(unsigned u) { return __uint_as_float(u << 16); }
; __device__ __forceinline__ float bfhi(unsigned u) { return __uint_as_float(u & 0xffff0000u); }
; __device__ __forceinline__ unsigned pk2(float lo, float hi) { f32x2_t v = {lo, hi}; bf16x2_t b = __builtin_convertvector(v, bf16x2_t); return __builtin_bit_cast(unsigned, b); }
; __device__ __forceinline__ void atomic_add_agent(float* p, float v) { (void)__hip_atomic_fetch_add(p, v, __ATOMIC_RELAXED, __HIP_MEMORY_SCOPE_AGENT); }
;     __device__ __forceinline__ void operator()(const f32x4 (&acc)[2][2][4][2], const pg8::Unit& u, int wr, int wc, int fr, int fq) const {
;     ...
;                 const int row = row0 + ai * 128 + m * 16; float s2 = 0.f;
; #pragma unroll
;                 for (int bj = 0; bj < 2; ++bj) {
;                     const size_t off = (size_t)row * 1024 + c0 + bj * 128;
;                     f32x4 x0, x1;
;                     if (xin) { x0 = *(const f32x4*)(xin + off); x1 = *(const f32x4*)(xin + off + 4); }
;                     else { const v4u xv = *(const v4u*)(xb + off); x0 = (f32x4){bflo(xv.x), bfhi(xv.x), bflo(xv.y), bfhi(xv.y)}; x1 = (f32x4){bflo(xv.z), bfhi(xv.z), bflo(xv.w), bfhi(xv.w)}; }
;                     const f32x4 n0 = x0 + acc[ai][bj][m][0], n1 = x1 + acc[ai][bj][m][1];
;                     if (xout) { *(f32x4*)(xout + off) = n0; *(f32x4*)(xout + off + 4) = n1; }
;                     else *(v4u*)(xb + off) = (v4u){pk2(n0[0], n0[1]), pk2(n0[2], n0[3]), pk2(n1[0], n1[1]), pk2(n1[2], n1[3])};
;                     s2 += ((n0[0] * n0[0] + n0[1] * n0[1]) + (n0[2] * n0[2] + n0[3] * n0[3])) + ((n1[0] * n1[0] + n1[1] * n1[1]) + (n1[2] * n1[2] + n1[3] * n1[3]));
;                 }
;                 if (ssq) { s2 += __shfl_xor(s2, 16); s2 += __shfl_xor(s2, 32); if (fq == 0) atomic_add_agent(ssq + row, s2); }
.LBB0_841:
	s_or_b64 exec, exec, s[2:3]
	v_add_u32_e32 v50, 0x90, v168
	s_waitcnt lgkmcnt(0)
	v_ashrrev_i32_e32 v51, 31, v50
	v_lshlrev_b64 v[52:53], 10, v[50:51]
	v_lshl_add_u64 v[52:53], v[52:53], 0, v[166:167]
	v_lshl_add_u64 v[56:57], v[52:53], 1, s[54:55]
	v_mov_b32_e32 v52, v44
	v_mov_b32_e32 v53, v45
	v_mov_b32_e32 v54, v42
	v_mov_b32_e32 v55, v43
	v_cvt_pk_bf16_f32 v42, v46, v47
	v_cvt_pk_bf16_f32 v43, v48, v49
	v_cvt_pk_bf16_f32 v44, v54, v55
	v_cvt_pk_bf16_f32 v45, v52, v53
	global_store_dwordx4 v[56:57], v[42:45], off
	s_nop 1
	v_mul_f32_e32 v42, v47, v47
	v_mul_f32_e32 v43, v49, v49
	v_fmac_f32_e32 v42, v46, v46
	v_fmac_f32_e32 v43, v48, v48
	v_add_f32_e32 v42, v42, v43
	v_mul_f32_e32 v43, v55, v55
	v_mul_f32_e32 v44, v53, v53
	v_fmac_f32_e32 v43, v54, v54
	v_fmac_f32_e32 v44, v52, v52
	v_add_f32_e32 v43, v43, v44
	v_add_f32_e32 v52, v42, v43
	v_mov_b32_e32 v42, v36
	v_mov_b32_e32 v43, v37
	v_mov_b32_e32 v44, v34
	v_mov_b32_e32 v45, v35
	v_cvt_pk_bf16_f32 v34, v38, v39
	v_cvt_pk_bf16_f32 v35, v40, v41
	v_cvt_pk_bf16_f32 v36, v44, v45
	v_cvt_pk_bf16_f32 v37, v42, v43
	global_store_dwordx4 v[56:57], v[34:37], off offset:256
	s_nop 1
	v_mul_f32_e32 v34, v39, v39
	v_mul_f32_e32 v35, v41, v41
	v_fmac_f32_e32 v34, v38, v38
	v_fmac_f32_e32 v35, v40, v40
	v_add_f32_e32 v34, v34, v35
	v_mul_f32_e32 v35, v45, v45
	v_mul_f32_e32 v36, v43, v43
	v_fmac_f32_e32 v35, v44, v44
	v_fmac_f32_e32 v36, v42, v42
	v_add_f32_e32 v35, v35, v36
	v_add_f32_e32 v34, v34, v35
	v_add_f32_e32 v34, v52, v34
	v_mov_b32_e32 v35, v34
	s_nop 1
	v_permlane16_swap_b32_e32 v35, v34
	s_waitcnt lgkmcnt(0)
	v_add_f32_e32 v34, v34, v35
	v_mov_b32_e32 v35, v34
	s_nop 1
	v_permlane32_swap_b32_e32 v35, v34
	s_and_saveexec_b64 s[2:3], s[0:1]
	s_cbranch_execz .LBB0_843
	v_readlane_b32 s20, v253, 11
	v_readlane_b32 s21, v253, 12
	s_waitcnt lgkmcnt(0)
	v_add_f32_e32 v34, v34, v35
	v_lshl_add_u64 v[36:37], v[50:51], 2, s[20:21]
	global_atomic_add_f32 v[36:37], v34, off
.LBB0_843:
	s_or_b64 exec, exec, s[2:3]
	v_add_u32_e32 v34, 0xa0, v168
	s_waitcnt lgkmcnt(0)
	v_ashrrev_i32_e32 v35, 31, v34
	v_lshlrev_b64 v[36:37], 10, v[34:35]
	v_lshl_add_u64 v[36:37], v[36:37], 0, v[166:167]
	v_lshl_add_u64 v[40:41], v[36:37], 1, s[54:55]
	v_mov_b32_e32 v36, v28
	v_mov_b32_e32 v37, v29
	v_mov_b32_e32 v38, v26
	v_mov_b32_e32 v39, v27
	v_cvt_pk_bf16_f32 v26, v30, v31
	v_cvt_pk_bf16_f32 v27, v32, v33
	v_cvt_pk_bf16_f32 v28, v38, v39
	v_cvt_pk_bf16_f32 v29, v36, v37
	global_store_dwordx4 v[40:41], v[26:29], off
	s_nop 1
	v_mul_f32_e32 v26, v31, v31
	v_mul_f32_e32 v27, v33, v33
	v_fmac_f32_e32 v26, v30, v30
	v_fmac_f32_e32 v27, v32, v32
	v_add_f32_e32 v26, v26, v27
	v_mul_f32_e32 v27, v39, v39
	v_mul_f32_e32 v28, v37, v37
	v_fmac_f32_e32 v27, v38, v38
	v_fmac_f32_e32 v28, v36, v36
	v_add_f32_e32 v27, v27, v28
	v_add_f32_e32 v36, v26, v27
	v_mov_b32_e32 v26, v20
	v_mov_b32_e32 v27, v21
	v_mov_b32_e32 v28, v18
	v_mov_b32_e32 v29, v19
	v_cvt_pk_bf16_f32 v18, v22, v23
	v_cvt_pk_bf16_f32 v19, v24, v25
	v_cvt_pk_bf16_f32 v20, v28, v29
	v_cvt_pk_bf16_f32 v21, v26, v27
	global_store_dwordx4 v[40:41], v[18:21], off offset:256
	s_nop 1
	v_mul_f32_e32 v18, v23, v23
	v_mul_f32_e32 v19, v25, v25
	v_fmac_f32_e32 v18, v22, v22
	v_fmac_f32_e32 v19, v24, v24
	v_add_f32_e32 v18, v18, v19
	v_mul_f32_e32 v19, v29, v29
	v_mul_f32_e32 v20, v27, v27
	v_fmac_f32_e32 v19, v28, v28
	v_fmac_f32_e32 v20, v26, v26
	v_add_f32_e32 v19, v19, v20
	v_add_f32_e32 v18, v18, v19
	v_add_f32_e32 v18, v36, v18
	v_mov_b32_e32 v19, v18
	s_nop 1
	v_permlane16_swap_b32_e32 v19, v18
	s_waitcnt lgkmcnt(0)
	v_add_f32_e32 v18, v18, v19
	v_mov_b32_e32 v19, v18
	s_nop 1
	v_permlane32_swap_b32_e32 v19, v18
	s_and_saveexec_b64 s[2:3], s[0:1]
	s_cbranch_execz .LBB0_845
	v_readlane_b32 s20, v253, 11
	v_readlane_b32 s21, v253, 12
	s_waitcnt lgkmcnt(0)
	v_add_f32_e32 v18, v18, v19
	v_lshl_add_u64 v[20:21], v[34:35], 2, s[20:21]
	global_atomic_add_f32 v[20:21], v18, off
.LBB0_845:
	s_or_b64 exec, exec, s[2:3]
	v_add_u32_e32 v18, 0xb0, v168
	s_waitcnt lgkmcnt(0)
	v_ashrrev_i32_e32 v19, 31, v18
	v_lshlrev_b64 v[20:21], 10, v[18:19]
	v_lshl_add_u64 v[20:21], v[20:21], 0, v[166:167]
	v_lshl_add_u64 v[24:25], v[20:21], 1, s[54:55]
	v_mov_b32_e32 v20, v12
	v_mov_b32_e32 v21, v13
	v_mov_b32_e32 v22, v10
	v_mov_b32_e32 v23, v11
	v_cvt_pk_bf16_f32 v10, v14, v15
	v_cvt_pk_bf16_f32 v11, v16, v17
	v_cvt_pk_bf16_f32 v12, v22, v23
	v_cvt_pk_bf16_f32 v13, v20, v21
	global_store_dwordx4 v[24:25], v[10:13], off
	s_nop 1
	v_mul_f32_e32 v10, v15, v15
	v_mul_f32_e32 v11, v17, v17
	v_fmac_f32_e32 v10, v14, v14
	v_fmac_f32_e32 v11, v16, v16
	v_add_f32_e32 v10, v10, v11
	v_mul_f32_e32 v11, v23, v23
	v_mul_f32_e32 v12, v21, v21
	v_fmac_f32_e32 v11, v22, v22
	v_fmac_f32_e32 v12, v20, v20
	v_add_f32_e32 v11, v11, v12
	v_add_f32_e32 v20, v10, v11
	v_mov_b32_e32 v10, v4
	v_mov_b32_e32 v11, v5
	v_mov_b32_e32 v12, v2
	v_mov_b32_e32 v13, v3
	v_cvt_pk_bf16_f32 v2, v6, v7
	v_cvt_pk_bf16_f32 v3, v8, v9
	v_cvt_pk_bf16_f32 v4, v12, v13
	v_cvt_pk_bf16_f32 v5, v10, v11
	global_store_dwordx4 v[24:25], v[2:5], off offset:256
	s_nop 1
	v_mul_f32_e32 v2, v7, v7
	v_mul_f32_e32 v3, v9, v9
	v_fmac_f32_e32 v2, v6, v6
	v_fmac_f32_e32 v3, v8, v8
	v_add_f32_e32 v2, v2, v3
	v_mul_f32_e32 v3, v13, v13
	v_mul_f32_e32 v4, v11, v11
	v_fmac_f32_e32 v3, v12, v12
	v_fmac_f32_e32 v4, v10, v10
	v_add_f32_e32 v3, v3, v4
	v_add_f32_e32 v2, v2, v3
	v_add_f32_e32 v2, v20, v2
	v_mov_b32_e32 v3, v2
	s_nop 1
	v_permlane16_swap_b32_e32 v3, v2
	s_waitcnt lgkmcnt(0)
	v_add_f32_e32 v2, v2, v3
	v_mov_b32_e32 v3, v2
	s_nop 1
	v_permlane32_swap_b32_e32 v3, v2
	s_and_saveexec_b64 s[2:3], s[0:1]
	s_cbranch_execz .LBB0_847
	v_readlane_b32 s20, v253, 11
	v_readlane_b32 s21, v253, 12
	s_waitcnt lgkmcnt(0)
	v_add_f32_e32 v2, v2, v3
	v_lshl_add_u64 v[4:5], v[18:19], 2, s[20:21]
	global_atomic_add_f32 v[4:5], v2, off

; __device__ __forceinline__ void atomic_add_agent(float* p, float v) { (void)__hip_atomic_fetch_add(p, v, __ATOMIC_RELAXED, __HIP_MEMORY_SCOPE_AGENT); }
;     __device__ __forceinline__ void operator()(const f32x4 (&acc)[2][2][4][2], const pg8::Unit& u, int wr, int wc, int fr, int fq) const {
;     ...
;                     s2 += ((n0[0] * n0[0] + n0[1] * n0[1]) + (n0[2] * n0[2] + n0[3] * n0[3])) + ((n1[0] * n1[0] + n1[1] * n1[1]) + (n1[2] * n1[2] + n1[3] * n1[3]));
;                 }
;                 if (ssq) { s2 += __shfl_xor(s2, 16); s2 += __shfl_xor(s2, 32); if (fq == 0) atomic_add_agent(ssq + row, s2); }
.LBB0_1394:
	v_readlane_b32 s2, v255, 33
	v_readlane_b32 s3, v255, 34
	s_andn2_b64 vcc, exec, s[2:3]
	s_nop 0
	v_cndmask_b32_e64 v130, 0, 1, s[2:3]
	v_cmp_ne_u32_e64 s[10:11], 1, v130
	s_cbranch_vccnz .LBB0_1398
	v_mul_f32_e32 v115, v115, v115
	v_mul_f32_e32 v127, v127, v127
	v_mul_f32_e32 v123, v123, v123
	v_mul_f32_e32 v119, v119, v119
	v_fmac_f32_e32 v115, v114, v114
	v_mul_f32_e32 v114, v117, v117
	v_fmac_f32_e32 v127, v126, v126
	v_mul_f32_e32 v126, v129, v129
	v_fmac_f32_e32 v123, v122, v122
	v_mul_f32_e32 v122, v125, v125
	v_fmac_f32_e32 v119, v118, v118
	v_mul_f32_e32 v118, v121, v121
	v_fmac_f32_e32 v114, v116, v116
	v_and_b32_e32 v116, 64, v191
	v_fmac_f32_e32 v126, v128, v128
	v_fmac_f32_e32 v122, v124, v124
	v_fmac_f32_e32 v118, v120, v120
	v_add_f32_e32 v114, v115, v114
	v_xor_b32_e32 v115, 16, v191
	v_add_u32_e32 v116, 64, v116
	v_add_f32_e32 v126, v127, v126
	v_add_f32_e32 v122, v123, v122
	v_add_f32_e32 v118, v119, v118
	v_cmp_lt_i32_e32 vcc, v115, v116
	v_add_f32_e32 v122, v122, v126
	v_add_f32_e32 v114, v114, v118
	v_cndmask_b32_e32 v115, v191, v115, vcc
	v_add_f32_e32 v114, v122, v114
	v_lshlrev_b32_e32 v115, 2, v115
	v_mov_b32_e32 v115, v114
	s_nop 1
	v_permlane16_swap_b32_e32 v115, v114
	s_waitcnt lgkmcnt(0)
	v_add_f32_e32 v114, v114, v115
	v_xor_b32_e32 v115, 32, v191
	v_cmp_lt_i32_e32 vcc, v115, v116
	s_nop 1
	v_cndmask_b32_e32 v115, v191, v115, vcc
	v_lshlrev_b32_e32 v115, 2, v115
	v_mov_b32_e32 v115, v114
	s_nop 1
	v_permlane32_swap_b32_e32 v115, v114
	s_and_saveexec_b64 s[2:3], s[0:1]
	s_cbranch_execz .LBB0_1397
	v_readlane_b32 s48, v251, 29
	v_readlane_b32 s49, v251, 30
	s_waitcnt lgkmcnt(0)
	v_add_f32_e32 v114, v114, v115
	v_lshl_add_u64 v[116:117], v[176:177], 2, s[48:49]
	global_atomic_add_f32 v[116:117], v114, off

; __device__ __forceinline__ void atomic_add_agent(float* p, float v) { (void)__hip_atomic_fetch_add(p, v, __ATOMIC_RELAXED, __HIP_MEMORY_SCOPE_AGENT); }
;     __device__ __forceinline__ void operator()(const f32x4 (&acc)[2][2][4][2], const pg8::Unit& u, int wr, int wc, int fr, int fq) const {
;     ...
;                     s2 += ((n0[0] * n0[0] + n0[1] * n0[1]) + (n0[2] * n0[2] + n0[3] * n0[3])) + ((n1[0] * n1[0] + n1[1] * n1[1]) + (n1[2] * n1[2] + n1[3] * n1[3]));
;                 }
;                 if (ssq) { s2 += __shfl_xor(s2, 16); s2 += __shfl_xor(s2, 32); if (fq == 0) atomic_add_agent(ssq + row, s2); }
.LBB0_1410:
	s_and_b64 vcc, exec, s[10:11]
	s_cbranch_vccnz .LBB0_1414
	v_mul_f32_e32 v99, v99, v99
	v_mul_f32_e32 v111, v111, v111
	v_mul_f32_e32 v107, v107, v107
	v_mul_f32_e32 v103, v103, v103
	v_fmac_f32_e32 v99, v98, v98
	v_mul_f32_e32 v98, v101, v101
	v_fmac_f32_e32 v111, v110, v110
	v_mul_f32_e32 v110, v113, v113
	v_fmac_f32_e32 v107, v106, v106
	v_mul_f32_e32 v106, v109, v109
	v_fmac_f32_e32 v103, v102, v102
	v_mul_f32_e32 v102, v105, v105
	v_fmac_f32_e32 v98, v100, v100
	v_and_b32_e32 v100, 64, v191
	v_fmac_f32_e32 v110, v112, v112
	v_fmac_f32_e32 v106, v108, v108
	v_fmac_f32_e32 v102, v104, v104
	v_add_f32_e32 v98, v99, v98
	v_xor_b32_e32 v99, 16, v191
	v_add_u32_e32 v100, 64, v100
	v_add_f32_e32 v110, v111, v110
	v_add_f32_e32 v106, v107, v106
	v_add_f32_e32 v102, v103, v102
	v_cmp_lt_i32_e32 vcc, v99, v100
	v_add_f32_e32 v106, v106, v110
	v_add_f32_e32 v98, v98, v102
	v_cndmask_b32_e32 v99, v191, v99, vcc
	v_add_f32_e32 v98, v106, v98
	v_lshlrev_b32_e32 v99, 2, v99
	v_mov_b32_e32 v99, v98
	s_nop 1
	v_permlane16_swap_b32_e32 v99, v98
	s_waitcnt lgkmcnt(0)
	v_add_f32_e32 v98, v98, v99
	v_xor_b32_e32 v99, 32, v191
	v_cmp_lt_i32_e32 vcc, v99, v100
	s_nop 1
	v_cndmask_b32_e32 v99, v191, v99, vcc
	v_lshlrev_b32_e32 v99, 2, v99
	v_mov_b32_e32 v99, v98
	s_nop 1
	v_permlane32_swap_b32_e32 v99, v98
	s_and_saveexec_b64 s[2:3], s[0:1]
	s_cbranch_execz .LBB0_1413
	v_readlane_b32 s48, v251, 29
	v_readlane_b32 s49, v251, 30
	s_waitcnt lgkmcnt(0)
	v_add_f32_e32 v98, v98, v99
	v_lshl_add_u64 v[100:101], v[122:123], 2, s[48:49]
	global_atomic_add_f32 v[100:101], v98, off

; __device__ __forceinline__ void atomic_add_agent(float* p, float v) { (void)__hip_atomic_fetch_add(p, v, __ATOMIC_RELAXED, __HIP_MEMORY_SCOPE_AGENT); }
;     __device__ __forceinline__ void operator()(const f32x4 (&acc)[2][2][4][2], const pg8::Unit& u, int wr, int wc, int fr, int fq) const {
;     ...
;                     s2 += ((n0[0] * n0[0] + n0[1] * n0[1]) + (n0[2] * n0[2] + n0[3] * n0[3])) + ((n1[0] * n1[0] + n1[1] * n1[1]) + (n1[2] * n1[2] + n1[3] * n1[3]));
;                 }
;                 if (ssq) { s2 += __shfl_xor(s2, 16); s2 += __shfl_xor(s2, 32); if (fq == 0) atomic_add_agent(ssq + row, s2); }
.LBB0_1426:
	s_and_b64 vcc, exec, s[10:11]
	s_cbranch_vccnz .LBB0_1430
	v_mul_f32_e32 v83, v83, v83
	v_mul_f32_e32 v95, v95, v95
	v_mul_f32_e32 v91, v91, v91
	v_mul_f32_e32 v87, v87, v87
	v_fmac_f32_e32 v83, v82, v82
	v_mul_f32_e32 v82, v85, v85
	v_fmac_f32_e32 v95, v94, v94
	v_mul_f32_e32 v94, v97, v97
	v_fmac_f32_e32 v91, v90, v90
	v_mul_f32_e32 v90, v93, v93
	v_fmac_f32_e32 v87, v86, v86
	v_mul_f32_e32 v86, v89, v89
	v_fmac_f32_e32 v82, v84, v84
	v_and_b32_e32 v84, 64, v191
	v_fmac_f32_e32 v94, v96, v96
	v_fmac_f32_e32 v90, v92, v92
	v_fmac_f32_e32 v86, v88, v88
	v_add_f32_e32 v82, v83, v82
	v_xor_b32_e32 v83, 16, v191
	v_add_u32_e32 v84, 64, v84
	v_add_f32_e32 v94, v95, v94
	v_add_f32_e32 v90, v91, v90
	v_add_f32_e32 v86, v87, v86
	v_cmp_lt_i32_e32 vcc, v83, v84
	v_add_f32_e32 v90, v90, v94
	v_add_f32_e32 v82, v82, v86
	v_cndmask_b32_e32 v83, v191, v83, vcc
	v_add_f32_e32 v82, v90, v82
	v_lshlrev_b32_e32 v83, 2, v83
	v_mov_b32_e32 v83, v82
	s_nop 1
	v_permlane16_swap_b32_e32 v83, v82
	s_waitcnt lgkmcnt(0)
	v_add_f32_e32 v82, v82, v83
	v_xor_b32_e32 v83, 32, v191
	v_cmp_lt_i32_e32 vcc, v83, v84
	s_nop 1
	v_cndmask_b32_e32 v83, v191, v83, vcc
	v_lshlrev_b32_e32 v83, 2, v83
	v_mov_b32_e32 v83, v82
	s_nop 1
	v_permlane32_swap_b32_e32 v83, v82
	s_and_saveexec_b64 s[2:3], s[0:1]
	s_cbranch_execz .LBB0_1429
	v_readlane_b32 s48, v251, 29
	v_readlane_b32 s49, v251, 30
	s_waitcnt lgkmcnt(0)
	v_add_f32_e32 v82, v82, v83
	v_lshl_add_u64 v[84:85], v[106:107], 2, s[48:49]
	global_atomic_add_f32 v[84:85], v82, off

; __device__ __forceinline__ void atomic_add_agent(float* p, float v) { (void)__hip_atomic_fetch_add(p, v, __ATOMIC_RELAXED, __HIP_MEMORY_SCOPE_AGENT); }
;     __device__ __forceinline__ void operator()(const f32x4 (&acc)[2][2][4][2], const pg8::Unit& u, int wr, int wc, int fr, int fq) const {
;     ...
;                     s2 += ((n0[0] * n0[0] + n0[1] * n0[1]) + (n0[2] * n0[2] + n0[3] * n0[3])) + ((n1[0] * n1[0] + n1[1] * n1[1]) + (n1[2] * n1[2] + n1[3] * n1[3]));
;                 }
;                 if (ssq) { s2 += __shfl_xor(s2, 16); s2 += __shfl_xor(s2, 32); if (fq == 0) atomic_add_agent(ssq + row, s2); }
.LBB0_1442:
	s_and_b64 vcc, exec, s[10:11]
	s_cbranch_vccnz .LBB0_1446
	v_mul_f32_e32 v67, v67, v67
	v_mul_f32_e32 v79, v79, v79
	v_mul_f32_e32 v75, v75, v75
	v_mul_f32_e32 v71, v71, v71
	v_fmac_f32_e32 v67, v66, v66
	v_mul_f32_e32 v66, v69, v69
	v_fmac_f32_e32 v79, v78, v78
	v_mul_f32_e32 v78, v81, v81
	v_fmac_f32_e32 v75, v74, v74
	v_mul_f32_e32 v74, v77, v77
	v_fmac_f32_e32 v71, v70, v70
	v_mul_f32_e32 v70, v73, v73
	v_fmac_f32_e32 v66, v68, v68
	v_and_b32_e32 v68, 64, v191
	v_fmac_f32_e32 v78, v80, v80
	v_fmac_f32_e32 v74, v76, v76
	v_fmac_f32_e32 v70, v72, v72
	v_add_f32_e32 v66, v67, v66
	v_xor_b32_e32 v67, 16, v191
	v_add_u32_e32 v68, 64, v68
	v_add_f32_e32 v78, v79, v78
	v_add_f32_e32 v74, v75, v74
	v_add_f32_e32 v70, v71, v70
	v_cmp_lt_i32_e32 vcc, v67, v68
	v_add_f32_e32 v74, v74, v78
	v_add_f32_e32 v66, v66, v70
	v_cndmask_b32_e32 v67, v191, v67, vcc
	v_add_f32_e32 v66, v74, v66
	v_lshlrev_b32_e32 v67, 2, v67
	v_mov_b32_e32 v67, v66
	s_nop 1
	v_permlane16_swap_b32_e32 v67, v66
	s_waitcnt lgkmcnt(0)
	v_add_f32_e32 v66, v66, v67
	v_xor_b32_e32 v67, 32, v191
	v_cmp_lt_i32_e32 vcc, v67, v68
	s_nop 1
	v_cndmask_b32_e32 v67, v191, v67, vcc
	v_lshlrev_b32_e32 v67, 2, v67
	v_mov_b32_e32 v67, v66
	s_nop 1
	v_permlane32_swap_b32_e32 v67, v66
	s_and_saveexec_b64 s[2:3], s[0:1]
	s_cbranch_execz .LBB0_1445
	v_readlane_b32 s48, v251, 29
	v_readlane_b32 s49, v251, 30
	s_waitcnt lgkmcnt(0)
	v_add_f32_e32 v66, v66, v67
	v_lshl_add_u64 v[68:69], v[90:91], 2, s[48:49]
	global_atomic_add_f32 v[68:69], v66, off

; __device__ __forceinline__ void atomic_add_agent(float* p, float v) { (void)__hip_atomic_fetch_add(p, v, __ATOMIC_RELAXED, __HIP_MEMORY_SCOPE_AGENT); }
;     __device__ __forceinline__ void operator()(const f32x4 (&acc)[2][2][4][2], const pg8::Unit& u, int wr, int wc, int fr, int fq) const {
;     ...
;                     s2 += ((n0[0] * n0[0] + n0[1] * n0[1]) + (n0[2] * n0[2] + n0[3] * n0[3])) + ((n1[0] * n1[0] + n1[1] * n1[1]) + (n1[2] * n1[2] + n1[3] * n1[3]));
;                 }
;                 if (ssq) { s2 += __shfl_xor(s2, 16); s2 += __shfl_xor(s2, 32); if (fq == 0) atomic_add_agent(ssq + row, s2); }
.LBB0_1458:
	s_and_b64 vcc, exec, s[10:11]
	s_cbranch_vccnz .LBB0_1462
	v_mul_f32_e32 v51, v51, v51
	v_mul_f32_e32 v63, v63, v63
	v_mul_f32_e32 v59, v59, v59
	v_mul_f32_e32 v55, v55, v55
	v_fmac_f32_e32 v51, v50, v50
	v_mul_f32_e32 v50, v53, v53
	v_fmac_f32_e32 v63, v62, v62
	v_mul_f32_e32 v62, v65, v65
	v_fmac_f32_e32 v59, v58, v58
	v_mul_f32_e32 v58, v61, v61
	v_fmac_f32_e32 v55, v54, v54
	v_mul_f32_e32 v54, v57, v57
	v_fmac_f32_e32 v50, v52, v52
	v_and_b32_e32 v52, 64, v191
	v_fmac_f32_e32 v62, v64, v64
	v_fmac_f32_e32 v58, v60, v60
	v_fmac_f32_e32 v54, v56, v56
	v_add_f32_e32 v50, v51, v50
	v_xor_b32_e32 v51, 16, v191
	v_add_u32_e32 v52, 64, v52
	v_add_f32_e32 v62, v63, v62
	v_add_f32_e32 v58, v59, v58
	v_add_f32_e32 v54, v55, v54
	v_cmp_lt_i32_e32 vcc, v51, v52
	v_add_f32_e32 v58, v58, v62
	v_add_f32_e32 v50, v50, v54
	v_cndmask_b32_e32 v51, v191, v51, vcc
	v_add_f32_e32 v50, v58, v50
	v_lshlrev_b32_e32 v51, 2, v51
	v_mov_b32_e32 v51, v50
	s_nop 1
	v_permlane16_swap_b32_e32 v51, v50
	s_waitcnt lgkmcnt(0)
	v_add_f32_e32 v50, v50, v51
	v_xor_b32_e32 v51, 32, v191
	v_cmp_lt_i32_e32 vcc, v51, v52
	s_nop 1
	v_cndmask_b32_e32 v51, v191, v51, vcc
	v_lshlrev_b32_e32 v51, 2, v51
	v_mov_b32_e32 v51, v50
	s_nop 1
	v_permlane32_swap_b32_e32 v51, v50
	s_and_saveexec_b64 s[2:3], s[0:1]
	s_cbranch_execz .LBB0_1461
	v_readlane_b32 s48, v251, 29
	v_readlane_b32 s49, v251, 30
	s_waitcnt lgkmcnt(0)
	v_add_f32_e32 v50, v50, v51
	v_lshl_add_u64 v[52:53], v[74:75], 2, s[48:49]
	global_atomic_add_f32 v[52:53], v50, off

; __device__ __forceinline__ void atomic_add_agent(float* p, float v) { (void)__hip_atomic_fetch_add(p, v, __ATOMIC_RELAXED, __HIP_MEMORY_SCOPE_AGENT); }
;     __device__ __forceinline__ void operator()(const f32x4 (&acc)[2][2][4][2], const pg8::Unit& u, int wr, int wc, int fr, int fq) const {
;     ...
;                     s2 += ((n0[0] * n0[0] + n0[1] * n0[1]) + (n0[2] * n0[2] + n0[3] * n0[3])) + ((n1[0] * n1[0] + n1[1] * n1[1]) + (n1[2] * n1[2] + n1[3] * n1[3]));
;                 }
;                 if (ssq) { s2 += __shfl_xor(s2, 16); s2 += __shfl_xor(s2, 32); if (fq == 0) atomic_add_agent(ssq + row, s2); }
.LBB0_1474:
	s_and_b64 vcc, exec, s[10:11]
	s_cbranch_vccnz .LBB0_1478
	v_mul_f32_e32 v35, v35, v35
	v_mul_f32_e32 v47, v47, v47
	v_mul_f32_e32 v43, v43, v43
	v_mul_f32_e32 v39, v39, v39
	v_fmac_f32_e32 v35, v34, v34
	v_mul_f32_e32 v34, v37, v37
	v_fmac_f32_e32 v47, v46, v46
	v_mul_f32_e32 v46, v49, v49
	v_fmac_f32_e32 v43, v42, v42
	v_mul_f32_e32 v42, v45, v45
	v_fmac_f32_e32 v39, v38, v38
	v_mul_f32_e32 v38, v41, v41
	v_fmac_f32_e32 v34, v36, v36
	v_and_b32_e32 v36, 64, v191
	v_fmac_f32_e32 v46, v48, v48
	v_fmac_f32_e32 v42, v44, v44
	v_fmac_f32_e32 v38, v40, v40
	v_add_f32_e32 v34, v35, v34
	v_xor_b32_e32 v35, 16, v191
	v_add_u32_e32 v36, 64, v36
	v_add_f32_e32 v46, v47, v46
	v_add_f32_e32 v42, v43, v42
	v_add_f32_e32 v38, v39, v38
	v_cmp_lt_i32_e32 vcc, v35, v36
	v_add_f32_e32 v42, v42, v46
	v_add_f32_e32 v34, v34, v38
	v_cndmask_b32_e32 v35, v191, v35, vcc
	v_add_f32_e32 v34, v42, v34
	v_lshlrev_b32_e32 v35, 2, v35
	v_mov_b32_e32 v35, v34
	s_nop 1
	v_permlane16_swap_b32_e32 v35, v34
	s_waitcnt lgkmcnt(0)
	v_add_f32_e32 v34, v34, v35
	v_xor_b32_e32 v35, 32, v191
	v_cmp_lt_i32_e32 vcc, v35, v36
	s_nop 1
	v_cndmask_b32_e32 v35, v191, v35, vcc
	v_lshlrev_b32_e32 v35, 2, v35
	v_mov_b32_e32 v35, v34
	s_nop 1
	v_permlane32_swap_b32_e32 v35, v34
	s_and_saveexec_b64 s[2:3], s[0:1]
	s_cbranch_execz .LBB0_1477
	v_readlane_b32 s48, v251, 29
	v_readlane_b32 s49, v251, 30
	s_waitcnt lgkmcnt(0)
	v_add_f32_e32 v34, v34, v35
	v_lshl_add_u64 v[36:37], v[58:59], 2, s[48:49]
	global_atomic_add_f32 v[36:37], v34, off

; __device__ __forceinline__ void atomic_add_agent(float* p, float v) { (void)__hip_atomic_fetch_add(p, v, __ATOMIC_RELAXED, __HIP_MEMORY_SCOPE_AGENT); }
;     __device__ __forceinline__ void operator()(const f32x4 (&acc)[2][2][4][2], const pg8::Unit& u, int wr, int wc, int fr, int fq) const {
;     ...
;                     s2 += ((n0[0] * n0[0] + n0[1] * n0[1]) + (n0[2] * n0[2] + n0[3] * n0[3])) + ((n1[0] * n1[0] + n1[1] * n1[1]) + (n1[2] * n1[2] + n1[3] * n1[3]));
;                 }
;                 if (ssq) { s2 += __shfl_xor(s2, 16); s2 += __shfl_xor(s2, 32); if (fq == 0) atomic_add_agent(ssq + row, s2); }
.LBB0_1490:
	s_and_b64 vcc, exec, s[10:11]
	s_cbranch_vccnz .LBB0_1494
	v_mul_f32_e32 v19, v19, v19
	v_mul_f32_e32 v31, v31, v31
	v_mul_f32_e32 v27, v27, v27
	v_mul_f32_e32 v23, v23, v23
	v_fmac_f32_e32 v19, v18, v18
	v_mul_f32_e32 v18, v21, v21
	v_fmac_f32_e32 v31, v30, v30
	v_mul_f32_e32 v30, v33, v33
	v_fmac_f32_e32 v27, v26, v26
	v_mul_f32_e32 v26, v29, v29
	v_fmac_f32_e32 v23, v22, v22
	v_mul_f32_e32 v22, v25, v25
	v_fmac_f32_e32 v18, v20, v20
	v_and_b32_e32 v20, 64, v191
	v_fmac_f32_e32 v30, v32, v32
	v_fmac_f32_e32 v26, v28, v28
	v_fmac_f32_e32 v22, v24, v24
	v_add_f32_e32 v18, v19, v18
	v_xor_b32_e32 v19, 16, v191
	v_add_u32_e32 v20, 64, v20
	v_add_f32_e32 v30, v31, v30
	v_add_f32_e32 v26, v27, v26
	v_add_f32_e32 v22, v23, v22
	v_cmp_lt_i32_e32 vcc, v19, v20
	v_add_f32_e32 v26, v26, v30
	v_add_f32_e32 v18, v18, v22
	v_cndmask_b32_e32 v19, v191, v19, vcc
	v_add_f32_e32 v18, v26, v18
	v_lshlrev_b32_e32 v19, 2, v19
	v_mov_b32_e32 v19, v18
	s_nop 1
	v_permlane16_swap_b32_e32 v19, v18
	s_waitcnt lgkmcnt(0)
	v_add_f32_e32 v18, v18, v19
	v_xor_b32_e32 v19, 32, v191
	v_cmp_lt_i32_e32 vcc, v19, v20
	s_nop 1
	v_cndmask_b32_e32 v19, v191, v19, vcc
	v_lshlrev_b32_e32 v19, 2, v19
	v_mov_b32_e32 v19, v18
	s_nop 1
	v_permlane32_swap_b32_e32 v19, v18
	s_and_saveexec_b64 s[2:3], s[0:1]
	s_cbranch_execz .LBB0_1493
	v_readlane_b32 s48, v251, 29
	v_readlane_b32 s49, v251, 30
	s_waitcnt lgkmcnt(0)
	v_add_f32_e32 v18, v18, v19
	v_lshl_add_u64 v[20:21], v[42:43], 2, s[48:49]
	global_atomic_add_f32 v[20:21], v18, off

; __device__ __forceinline__ void atomic_add_agent(float* p, float v) { (void)__hip_atomic_fetch_add(p, v, __ATOMIC_RELAXED, __HIP_MEMORY_SCOPE_AGENT); }
;     __device__ __forceinline__ void operator()(const f32x4 (&acc)[2][2][4][2], const pg8::Unit& u, int wr, int wc, int fr, int fq) const {
;     ...
;                     s2 += ((n0[0] * n0[0] + n0[1] * n0[1]) + (n0[2] * n0[2] + n0[3] * n0[3])) + ((n1[0] * n1[0] + n1[1] * n1[1]) + (n1[2] * n1[2] + n1[3] * n1[3]));
;                 }
;                 if (ssq) { s2 += __shfl_xor(s2, 16); s2 += __shfl_xor(s2, 32); if (fq == 0) atomic_add_agent(ssq + row, s2); }
.LBB0_1508:
	v_mul_f32_e32 v3, v3, v3
	v_mul_f32_e32 v15, v15, v15
	v_mul_f32_e32 v11, v11, v11
	v_mul_f32_e32 v7, v7, v7
	v_fmac_f32_e32 v3, v2, v2
	v_mul_f32_e32 v2, v5, v5
	v_fmac_f32_e32 v15, v14, v14
	v_mul_f32_e32 v14, v17, v17
	v_fmac_f32_e32 v11, v10, v10
	v_mul_f32_e32 v10, v13, v13
	v_fmac_f32_e32 v7, v6, v6
	v_mul_f32_e32 v6, v9, v9
	v_fmac_f32_e32 v2, v4, v4
	v_and_b32_e32 v4, 64, v191
	v_fmac_f32_e32 v14, v16, v16
	v_fmac_f32_e32 v10, v12, v12
	v_fmac_f32_e32 v6, v8, v8
	v_add_f32_e32 v2, v3, v2
	v_xor_b32_e32 v3, 16, v191
	v_add_u32_e32 v4, 64, v4
	v_add_f32_e32 v14, v15, v14
	v_add_f32_e32 v10, v11, v10
	v_add_f32_e32 v6, v7, v6
	v_cmp_lt_i32_e32 vcc, v3, v4
	v_add_f32_e32 v10, v10, v14
	v_add_f32_e32 v2, v2, v6
	v_cndmask_b32_e32 v3, v191, v3, vcc
	v_add_f32_e32 v2, v10, v2
	v_lshlrev_b32_e32 v3, 2, v3
	v_mov_b32_e32 v3, v2
	s_nop 1
	v_permlane16_swap_b32_e32 v3, v2
	s_waitcnt lgkmcnt(0)
	v_add_f32_e32 v2, v2, v3
	v_xor_b32_e32 v3, 32, v191
	v_cmp_lt_i32_e32 vcc, v3, v4
	s_nop 1
	v_cndmask_b32_e32 v3, v191, v3, vcc
	v_lshlrev_b32_e32 v3, 2, v3
	v_mov_b32_e32 v3, v2
	s_nop 1
	v_permlane32_swap_b32_e32 v3, v2
	s_and_saveexec_b64 s[2:3], s[0:1]
	s_cbranch_execz .LBB0_1510
	v_readlane_b32 s6, v251, 29
	v_readlane_b32 s7, v251, 30
	s_waitcnt lgkmcnt(0)
	v_add_f32_e32 v2, v2, v3
	v_lshl_add_u64 v[4:5], v[26:27], 2, s[6:7]
	global_atomic_add_f32 v[4:5], v2, off
